# phase 0 filter output layer on the f32 matrix cores (v_mfma_f32_32x32x2_f32; f32 operands and accumulate), barrier before the h2 reads kept; cache conversion loops straight-lined
# speedup vs baseline: 1.0393x; 1.0045x over previous
.LBB0_747:
	s_cmpk_gt_i32 s7, 0x10f
	s_mov_b64 s[0:1], -1
	s_cbranch_scc0 .LBB0_829
	s_cmpk_gt_u32 s7, 0x1cf
	s_cbranch_scc0 .LBB0_814
	s_cmpk_gt_u32 s7, 0x36f
	s_cbranch_scc0 .LBB0_806
	s_cmpk_gt_u32 s7, 0x3ef
	s_cbranch_scc0 .LBB0_803
	s_cmpk_gt_u32 s7, 0x5ef
	s_cbranch_scc0 .LBB0_799
	v_readlane_b32 s0, v255, 27
	s_mul_i32 s0, s0, s4
	v_readlane_b32 s1, v255, 25
	s_add_i32 s8, s1, s0
	s_lshl_b32 s0, s7, 8
	s_add_i32 s0, s0, 0xfffa1000
	v_mov_b32_e32 v10, v151
	s_nop 0
	v_add_u32_e32 v2, s0, v10
	v_readlane_b32 s56, v252, 17
	v_readlane_b32 s57, v252, 18
	v_readlane_b32 s58, v252, 19
	v_readlane_b32 s59, v252, 20
	v_readlane_b32 s60, v252, 21
	v_readlane_b32 s61, v252, 22
	v_readlane_b32 s62, v252, 23
	v_readlane_b32 s63, v252, 24
	v_lshlrev_b32_e32 v20, 2, v2
	v_and_b32_e32 v0, 0x1ff, v2
	v_lshrrev_b32_e32 v3, 9, v2
	v_lshl_add_u32 v21, v0, 7, v3
	v_lshlrev_b32_e32 v21, 2, v21
	v_lshl_add_u32 v22, v0, 8, v3
	v_lshlrev_b32_e32 v22, 2, v22
	v_lshlrev_b32_e32 v23, 1, v2
	v_mov_b32_e32 v24, v20
	global_load_dword v32, v24, s[56:57]
	v_add_u32_e32 v24, 0x40000, v24
	global_load_dword v33, v24, s[56:57]
	v_add_u32_e32 v24, 0x40000, v24
	global_load_dword v34, v24, s[56:57]
	v_add_u32_e32 v24, 0x40000, v24
	global_load_dword v35, v24, s[56:57]
	v_add_u32_e32 v24, 0x40000, v24
	global_load_dword v36, v24, s[56:57]
	v_add_u32_e32 v24, 0x40000, v24
	global_load_dword v37, v24, s[56:57]
	v_add_u32_e32 v24, 0x40000, v24
	global_load_dword v38, v24, s[56:57]
	v_add_u32_e32 v24, 0x40000, v24
	global_load_dword v39, v24, s[56:57]
	v_mov_b32_e32 v24, v21
	global_load_dword v40, v24, s[58:59]
	v_add_u32_e32 v24, 0x40000, v24
	global_load_dword v41, v24, s[58:59]
	v_add_u32_e32 v24, 0x40000, v24
	global_load_dword v42, v24, s[58:59]
	v_add_u32_e32 v24, 0x40000, v24
	global_load_dword v43, v24, s[58:59]
	v_add_u32_e32 v24, 0x40000, v24
	global_load_dword v44, v24, s[58:59]
	v_add_u32_e32 v24, 0x40000, v24
	global_load_dword v45, v24, s[58:59]
	v_add_u32_e32 v24, 0x40000, v24
	global_load_dword v46, v24, s[58:59]
	v_add_u32_e32 v24, 0x40000, v24
	global_load_dword v47, v24, s[58:59]
	v_mov_b32_e32 v24, v20
	global_load_dword v48, v24, s[60:61]
	v_add_u32_e32 v24, 0x40000, v24
	global_load_dword v49, v24, s[60:61]
	v_add_u32_e32 v24, 0x40000, v24
	global_load_dword v50, v24, s[60:61]
	v_add_u32_e32 v24, 0x40000, v24
	global_load_dword v51, v24, s[60:61]
	v_add_u32_e32 v24, 0x40000, v24
	global_load_dword v52, v24, s[60:61]
	v_add_u32_e32 v24, 0x40000, v24
	global_load_dword v53, v24, s[60:61]
	v_add_u32_e32 v24, 0x40000, v24
	global_load_dword v54, v24, s[60:61]
	v_add_u32_e32 v24, 0x40000, v24
	global_load_dword v55, v24, s[60:61]
	v_add_u32_e32 v24, 0x40000, v24
	global_load_dword v56, v24, s[60:61]
	v_add_u32_e32 v24, 0x40000, v24
	global_load_dword v57, v24, s[60:61]
	v_add_u32_e32 v24, 0x40000, v24
	global_load_dword v58, v24, s[60:61]
	v_add_u32_e32 v24, 0x40000, v24
	global_load_dword v59, v24, s[60:61]
	v_add_u32_e32 v24, 0x40000, v24
	global_load_dword v60, v24, s[60:61]
	v_add_u32_e32 v24, 0x40000, v24
	global_load_dword v61, v24, s[60:61]
	v_add_u32_e32 v24, 0x40000, v24
	global_load_dword v62, v24, s[60:61]
	v_add_u32_e32 v24, 0x40000, v24
	global_load_dword v63, v24, s[60:61]
	v_mov_b32_e32 v24, v22
	global_load_dword v64, v24, s[62:63]
	global_load_dword v65, v24, s[62:63] offset:512
	v_add_u32_e32 v24, 0x80000, v24
	global_load_dword v66, v24, s[62:63]
	global_load_dword v67, v24, s[62:63] offset:512
	v_add_u32_e32 v24, 0x80000, v24
	global_load_dword v68, v24, s[62:63]
	global_load_dword v69, v24, s[62:63] offset:512
	v_add_u32_e32 v24, 0x80000, v24
	global_load_dword v70, v24, s[62:63]
	global_load_dword v71, v24, s[62:63] offset:512
	v_add_u32_e32 v24, 0x80000, v24
	global_load_dword v72, v24, s[62:63]
	global_load_dword v73, v24, s[62:63] offset:512
	v_add_u32_e32 v24, 0x80000, v24
	global_load_dword v74, v24, s[62:63]
	global_load_dword v75, v24, s[62:63] offset:512
	v_add_u32_e32 v24, 0x80000, v24
	global_load_dword v76, v24, s[62:63]
	global_load_dword v77, v24, s[62:63] offset:512
	v_add_u32_e32 v24, 0x80000, v24
	global_load_dword v78, v24, s[62:63]
	global_load_dword v79, v24, s[62:63] offset:512
	s_waitcnt vmcnt(46)
	v_cvt_pk_bf16_f32 v80, v32, v33
	s_waitcnt vmcnt(44)
	v_cvt_pk_bf16_f32 v81, v34, v35
	s_waitcnt vmcnt(42)
	v_cvt_pk_bf16_f32 v82, v36, v37
	s_waitcnt vmcnt(40)
	v_cvt_pk_bf16_f32 v83, v38, v39
	s_waitcnt vmcnt(38)
	v_cvt_pk_bf16_f32 v84, v40, v41
	s_waitcnt vmcnt(36)
	v_cvt_pk_bf16_f32 v85, v42, v43
	s_waitcnt vmcnt(34)
	v_cvt_pk_bf16_f32 v86, v44, v45
	s_waitcnt vmcnt(32)
	v_cvt_pk_bf16_f32 v87, v46, v47
	s_waitcnt vmcnt(30)
	v_cvt_pk_bf16_f32 v88, v48, v49
	s_waitcnt vmcnt(28)
	v_cvt_pk_bf16_f32 v89, v50, v51
	s_waitcnt vmcnt(26)
	v_cvt_pk_bf16_f32 v90, v52, v53
	s_waitcnt vmcnt(24)
	v_cvt_pk_bf16_f32 v91, v54, v55
	s_waitcnt vmcnt(22)
	v_cvt_pk_bf16_f32 v92, v56, v57
	s_waitcnt vmcnt(20)
	v_cvt_pk_bf16_f32 v93, v58, v59
	s_waitcnt vmcnt(18)
	v_cvt_pk_bf16_f32 v94, v60, v61
	s_waitcnt vmcnt(16)
	v_cvt_pk_bf16_f32 v95, v62, v63
	s_waitcnt vmcnt(14)
	v_cvt_pk_bf16_f32 v96, v64, v65
	s_waitcnt vmcnt(12)
	v_cvt_pk_bf16_f32 v97, v66, v67
	s_waitcnt vmcnt(10)
	v_cvt_pk_bf16_f32 v98, v68, v69
	s_waitcnt vmcnt(8)
	v_cvt_pk_bf16_f32 v99, v70, v71
	s_waitcnt vmcnt(6)
	v_cvt_pk_bf16_f32 v100, v72, v73
	s_waitcnt vmcnt(4)
	v_cvt_pk_bf16_f32 v101, v74, v75
	s_waitcnt vmcnt(2)
	v_cvt_pk_bf16_f32 v102, v76, v77
	s_waitcnt vmcnt(0)
	v_cvt_pk_bf16_f32 v103, v78, v79
	s_add_u32 s10, s94, 0xf500000
	s_addc_u32 s11, s95, 0
	v_mov_b32_e32 v24, v23
	global_store_short v24, v80, s[10:11]
	v_add_u32_e32 v24, 0x20000, v24
	global_store_short_d16_hi v24, v80, s[10:11]
	v_add_u32_e32 v24, 0x20000, v24
	global_store_short v24, v81, s[10:11]
	v_add_u32_e32 v24, 0x20000, v24
	global_store_short_d16_hi v24, v81, s[10:11]
	v_add_u32_e32 v24, 0x20000, v24
	global_store_short v24, v82, s[10:11]
	v_add_u32_e32 v24, 0x20000, v24
	global_store_short_d16_hi v24, v82, s[10:11]
	v_add_u32_e32 v24, 0x20000, v24
	global_store_short v24, v83, s[10:11]
	v_add_u32_e32 v24, 0x20000, v24
	global_store_short_d16_hi v24, v83, s[10:11]
	s_add_u32 s10, s94, 0xf600000
	s_addc_u32 s11, s95, 0
	v_mov_b32_e32 v24, v23
	global_store_short v24, v84, s[10:11]
	v_add_u32_e32 v24, 0x20000, v24
	global_store_short_d16_hi v24, v84, s[10:11]
	v_add_u32_e32 v24, 0x20000, v24
	global_store_short v24, v85, s[10:11]
	v_add_u32_e32 v24, 0x20000, v24
	global_store_short_d16_hi v24, v85, s[10:11]
	v_add_u32_e32 v24, 0x20000, v24
	global_store_short v24, v86, s[10:11]
	v_add_u32_e32 v24, 0x20000, v24
	global_store_short_d16_hi v24, v86, s[10:11]
	v_add_u32_e32 v24, 0x20000, v24
	global_store_short v24, v87, s[10:11]
	v_add_u32_e32 v24, 0x20000, v24
	global_store_short_d16_hi v24, v87, s[10:11]
	s_add_u32 s10, s94, 0xf700000
	s_addc_u32 s11, s95, 0
	v_mov_b32_e32 v24, v23
	global_store_short v24, v88, s[10:11]
	v_add_u32_e32 v24, 0x20000, v24
	global_store_short_d16_hi v24, v88, s[10:11]
	v_add_u32_e32 v24, 0x20000, v24
	global_store_short v24, v89, s[10:11]
	v_add_u32_e32 v24, 0x20000, v24
	global_store_short_d16_hi v24, v89, s[10:11]
	v_add_u32_e32 v24, 0x20000, v24
	global_store_short v24, v90, s[10:11]
	v_add_u32_e32 v24, 0x20000, v24
	global_store_short_d16_hi v24, v90, s[10:11]
	v_add_u32_e32 v24, 0x20000, v24
	global_store_short v24, v91, s[10:11]
	v_add_u32_e32 v24, 0x20000, v24
	global_store_short_d16_hi v24, v91, s[10:11]
	v_add_u32_e32 v24, 0x20000, v24
	global_store_short v24, v92, s[10:11]
	v_add_u32_e32 v24, 0x20000, v24
	global_store_short_d16_hi v24, v92, s[10:11]
	v_add_u32_e32 v24, 0x20000, v24
	global_store_short v24, v93, s[10:11]
	v_add_u32_e32 v24, 0x20000, v24
	global_store_short_d16_hi v24, v93, s[10:11]
	v_add_u32_e32 v24, 0x20000, v24
	global_store_short v24, v94, s[10:11]
	v_add_u32_e32 v24, 0x20000, v24
	global_store_short_d16_hi v24, v94, s[10:11]
	v_add_u32_e32 v24, 0x20000, v24
	global_store_short v24, v95, s[10:11]
	v_add_u32_e32 v24, 0x20000, v24
	global_store_short_d16_hi v24, v95, s[10:11]
	s_add_u32 s10, s94, 0xf900000
	s_addc_u32 s11, s95, 0
	v_mov_b32_e32 v24, v23
	global_store_short v24, v96, s[10:11]
	v_add_u32_e32 v24, 0x20000, v24
	global_store_short_d16_hi v24, v96, s[10:11]
	v_add_u32_e32 v24, 0x20000, v24
	global_store_short v24, v97, s[10:11]
	v_add_u32_e32 v24, 0x20000, v24
	global_store_short_d16_hi v24, v97, s[10:11]
	v_add_u32_e32 v24, 0x20000, v24
	global_store_short v24, v98, s[10:11]
	v_add_u32_e32 v24, 0x20000, v24
	global_store_short_d16_hi v24, v98, s[10:11]
	v_add_u32_e32 v24, 0x20000, v24
	global_store_short v24, v99, s[10:11]
	v_add_u32_e32 v24, 0x20000, v24
	global_store_short_d16_hi v24, v99, s[10:11]
	v_add_u32_e32 v24, 0x20000, v24
	global_store_short v24, v100, s[10:11]
	v_add_u32_e32 v24, 0x20000, v24
	global_store_short_d16_hi v24, v100, s[10:11]
	v_add_u32_e32 v24, 0x20000, v24
	global_store_short v24, v101, s[10:11]
	v_add_u32_e32 v24, 0x20000, v24
	global_store_short_d16_hi v24, v101, s[10:11]
	v_add_u32_e32 v24, 0x20000, v24
	global_store_short v24, v102, s[10:11]
	v_add_u32_e32 v24, 0x20000, v24
	global_store_short_d16_hi v24, v102, s[10:11]
	v_add_u32_e32 v24, 0x20000, v24
	global_store_short v24, v103, s[10:11]
	v_add_u32_e32 v24, 0x20000, v24
	global_store_short_d16_hi v24, v103, s[10:11]
	s_mov_b64 s[0:1], exec
	s_branch .LBB0_768
	s_mov_b32 s0, 0x80000
	v_cmp_gt_i32_e32 vcc, s0, v2
	s_and_saveexec_b64 s[0:1], vcc
	s_cbranch_execz .LBB0_760
	v_max_i32_e32 v0, 0x70000, v2
	v_add_u32_e32 v0, s8, v0
	v_sub_u32_e32 v6, v0, v10
	s_mov_b32 s9, 0xffff
	v_cmp_lt_u32_e32 vcc, s9, v6
	s_mov_b64 s[38:39], -1
	v_mov_b32_e32 v4, v2
	s_and_saveexec_b64 s[28:29], vcc
	s_cbranch_execz .LBB0_757
	v_add_u32_e32 v0, s6, v10
	v_max_i32_e32 v0, 0x70000, v0
	v_add_u32_e32 v0, s5, v0
	v_sub_u32_e32 v0, v0, v10
	v_add_u32_e32 v3, 0x10000, v2
	v_add_u32_sdwa v0, v0, v180 dst_sel:DWORD dst_unused:UNUSED_PAD src0_sel:WORD_1 src1_sel:DWORD
	v_readlane_b32 s52, v252, 13
	v_readlane_b32 s10, v253, 12
	v_readlane_b32 s12, v253, 14
	v_and_b32_e32 v7, 0x1fffe, v0
	s_mov_b64 s[38:39], 0
	v_mov_b64_e32 v[4:5], v[2:3]
	v_readlane_b32 s56, v252, 17
	v_readlane_b32 s57, v252, 18
	v_readlane_b32 s58, v252, 19
	v_readlane_b32 s59, v252, 20
	v_readlane_b32 s11, v253, 13
	v_readlane_b32 s13, v253, 15
	v_readlane_b32 s53, v252, 14
	v_readlane_b32 s54, v252, 15
	v_readlane_b32 s55, v252, 16
	v_readlane_b32 s60, v252, 21
	v_readlane_b32 s61, v252, 22
	v_readlane_b32 s62, v252, 23
	v_readlane_b32 s63, v252, 24
	v_readlane_b32 s64, v252, 25
	v_readlane_b32 s65, v252, 26
	v_readlane_b32 s66, v252, 27
	v_readlane_b32 s67, v252, 28

.LBB0_859:
	s_ashr_i32 s45, s44, 31
	v_readlane_b32 s52, v252, 45
	s_lshl_b64 s[0:1], s[44:45], 17
	v_readlane_b32 s66, v252, 59
	v_readlane_b32 s67, v252, 60
	s_add_u32 s0, s66, s0
	s_addc_u32 s1, s67, s1
	s_lshl_b32 s8, s7, 8
	s_and_b32 s8, s8, 0x100
	v_add_u32_e32 v2, s8, v142
	v_ashrrev_i32_e32 v3, 31, v2
	v_lshl_add_u64 v[20:21], v[2:3], 2, s[0:1]
	s_waitcnt vmcnt(0)
	v_and_b32_e32 v2, 31, v142
	v_bfe_u32 v3, v142, 5, 1
	v_and_b32_e32 v4, 0xc0, v142
	v_mul_u32_u24_e32 v5, 0xff80, v3
	v_add_co_u32_e32 v6, vcc, v20, v5
	s_nop 0
	v_addc_co_u32_e32 v7, vcc, 0, v21, vcc
	global_load_dword v18, v[6:7], off
	global_load_dword v50, v[6:7], off offset:128
	v_add_co_u32_e32 v6, vcc, 0x800, v6
	s_nop 0
	v_addc_co_u32_e32 v7, vcc, 0, v7, vcc
	global_load_dword v19, v[6:7], off
	global_load_dword v51, v[6:7], off offset:128
	v_add_co_u32_e32 v6, vcc, 0x800, v6
	s_nop 0
	v_addc_co_u32_e32 v7, vcc, 0, v7, vcc
	global_load_dword v20, v[6:7], off
	global_load_dword v52, v[6:7], off offset:128
	v_add_co_u32_e32 v6, vcc, 0x800, v6
	s_nop 0
	v_addc_co_u32_e32 v7, vcc, 0, v7, vcc
	global_load_dword v21, v[6:7], off
	global_load_dword v53, v[6:7], off offset:128
	v_add_co_u32_e32 v6, vcc, 0x800, v6
	s_nop 0
	v_addc_co_u32_e32 v7, vcc, 0, v7, vcc
	global_load_dword v22, v[6:7], off
	global_load_dword v54, v[6:7], off offset:128
	v_add_co_u32_e32 v6, vcc, 0x800, v6
	s_nop 0
	v_addc_co_u32_e32 v7, vcc, 0, v7, vcc
	global_load_dword v23, v[6:7], off
	global_load_dword v55, v[6:7], off offset:128
	v_add_co_u32_e32 v6, vcc, 0x800, v6
	s_nop 0
	v_addc_co_u32_e32 v7, vcc, 0, v7, vcc
	global_load_dword v24, v[6:7], off
	global_load_dword v56, v[6:7], off offset:128
	v_add_co_u32_e32 v6, vcc, 0x800, v6
	s_nop 0
	v_addc_co_u32_e32 v7, vcc, 0, v7, vcc
	global_load_dword v25, v[6:7], off
	global_load_dword v57, v[6:7], off offset:128
	v_add_co_u32_e32 v6, vcc, 0x800, v6
	s_nop 0
	v_addc_co_u32_e32 v7, vcc, 0, v7, vcc
	global_load_dword v26, v[6:7], off
	global_load_dword v58, v[6:7], off offset:128
	v_add_co_u32_e32 v6, vcc, 0x800, v6
	s_nop 0
	v_addc_co_u32_e32 v7, vcc, 0, v7, vcc
	global_load_dword v27, v[6:7], off
	global_load_dword v59, v[6:7], off offset:128
	v_add_co_u32_e32 v6, vcc, 0x800, v6
	s_nop 0
	v_addc_co_u32_e32 v7, vcc, 0, v7, vcc
	global_load_dword v28, v[6:7], off
	global_load_dword v60, v[6:7], off offset:128
	v_add_co_u32_e32 v6, vcc, 0x800, v6
	s_nop 0
	v_addc_co_u32_e32 v7, vcc, 0, v7, vcc
	global_load_dword v29, v[6:7], off
	global_load_dword v61, v[6:7], off offset:128
	v_add_co_u32_e32 v6, vcc, 0x800, v6
	s_nop 0
	v_addc_co_u32_e32 v7, vcc, 0, v7, vcc
	global_load_dword v30, v[6:7], off
	global_load_dword v62, v[6:7], off offset:128
	v_add_co_u32_e32 v6, vcc, 0x800, v6
	s_nop 0
	v_addc_co_u32_e32 v7, vcc, 0, v7, vcc
	global_load_dword v31, v[6:7], off
	global_load_dword v63, v[6:7], off offset:128
	v_add_co_u32_e32 v6, vcc, 0x800, v6
	s_nop 0
	v_addc_co_u32_e32 v7, vcc, 0, v7, vcc
	global_load_dword v32, v[6:7], off
	global_load_dword v64, v[6:7], off offset:128
	v_add_co_u32_e32 v6, vcc, 0x800, v6
	s_nop 0
	v_addc_co_u32_e32 v7, vcc, 0, v7, vcc
	global_load_dword v33, v[6:7], off
	global_load_dword v65, v[6:7], off offset:128
	v_add_co_u32_e32 v6, vcc, 0x800, v6
	s_nop 0
	v_addc_co_u32_e32 v7, vcc, 0, v7, vcc
	global_load_dword v34, v[6:7], off
	global_load_dword v66, v[6:7], off offset:128
	v_add_co_u32_e32 v6, vcc, 0x800, v6
	s_nop 0
	v_addc_co_u32_e32 v7, vcc, 0, v7, vcc
	global_load_dword v35, v[6:7], off
	global_load_dword v67, v[6:7], off offset:128
	v_add_co_u32_e32 v6, vcc, 0x800, v6
	s_nop 0
	v_addc_co_u32_e32 v7, vcc, 0, v7, vcc
	global_load_dword v36, v[6:7], off
	global_load_dword v68, v[6:7], off offset:128
	v_add_co_u32_e32 v6, vcc, 0x800, v6
	s_nop 0
	v_addc_co_u32_e32 v7, vcc, 0, v7, vcc
	global_load_dword v37, v[6:7], off
	global_load_dword v69, v[6:7], off offset:128
	v_add_co_u32_e32 v6, vcc, 0x800, v6
	s_nop 0
	v_addc_co_u32_e32 v7, vcc, 0, v7, vcc
	global_load_dword v38, v[6:7], off
	global_load_dword v70, v[6:7], off offset:128
	v_add_co_u32_e32 v6, vcc, 0x800, v6
	s_nop 0
	v_addc_co_u32_e32 v7, vcc, 0, v7, vcc
	global_load_dword v39, v[6:7], off
	global_load_dword v71, v[6:7], off offset:128
	v_add_co_u32_e32 v6, vcc, 0x800, v6
	s_nop 0
	v_addc_co_u32_e32 v7, vcc, 0, v7, vcc
	global_load_dword v40, v[6:7], off
	global_load_dword v72, v[6:7], off offset:128
	v_add_co_u32_e32 v6, vcc, 0x800, v6
	s_nop 0
	v_addc_co_u32_e32 v7, vcc, 0, v7, vcc
	global_load_dword v41, v[6:7], off
	global_load_dword v73, v[6:7], off offset:128
	v_add_co_u32_e32 v6, vcc, 0x800, v6
	s_nop 0
	v_addc_co_u32_e32 v7, vcc, 0, v7, vcc
	global_load_dword v42, v[6:7], off
	global_load_dword v74, v[6:7], off offset:128
	v_add_co_u32_e32 v6, vcc, 0x800, v6
	s_nop 0
	v_addc_co_u32_e32 v7, vcc, 0, v7, vcc
	global_load_dword v43, v[6:7], off
	global_load_dword v75, v[6:7], off offset:128
	v_add_co_u32_e32 v6, vcc, 0x800, v6
	s_nop 0
	v_addc_co_u32_e32 v7, vcc, 0, v7, vcc
	global_load_dword v44, v[6:7], off
	global_load_dword v76, v[6:7], off offset:128
	v_add_co_u32_e32 v6, vcc, 0x800, v6
	s_nop 0
	v_addc_co_u32_e32 v7, vcc, 0, v7, vcc
	global_load_dword v45, v[6:7], off
	global_load_dword v77, v[6:7], off offset:128
	v_add_co_u32_e32 v6, vcc, 0x800, v6
	s_nop 0
	v_addc_co_u32_e32 v7, vcc, 0, v7, vcc
	global_load_dword v46, v[6:7], off
	global_load_dword v78, v[6:7], off offset:128
	v_add_co_u32_e32 v6, vcc, 0x800, v6
	s_nop 0
	v_addc_co_u32_e32 v7, vcc, 0, v7, vcc
	global_load_dword v47, v[6:7], off
	global_load_dword v79, v[6:7], off offset:128
	v_add_co_u32_e32 v6, vcc, 0x800, v6
	s_nop 0
	v_addc_co_u32_e32 v7, vcc, 0, v7, vcc
	global_load_dword v48, v[6:7], off
	global_load_dword v80, v[6:7], off offset:128
	s_waitcnt vmcnt(61)
	v_add_co_u32_e32 v6, vcc, 0x800, v6
	s_nop 0
	v_addc_co_u32_e32 v7, vcc, 0, v7, vcc
	global_load_dword v49, v[6:7], off
	global_load_dword v81, v[6:7], off offset:128
	v_lshlrev_b32_e32 v118, 8, v2
	v_lshl_add_u32 v118, v3, 7, v118
	v_add_u32_e32 v118, 0x6100, v118
	v_lshlrev_b32_e32 v119, 2, v4
	v_lshl_add_u32 v119, v3, 4, v119
	v_add_u32_e32 v5, v4, v2
	v_mul_u32_u24_e32 v5, 0x90, v5
	v_lshl_add_u32 v120, v3, 3, v5
	v_add_u32_e32 v120, 0xa100, v120
	v_and_b32_e32 v5, 63, v142
	v_or_b32_e32 v5, s38, v5
	v_cvt_f32_i32_e32 v5, v5
	v_xor_b32_e32 v5, 0x80000000, v5
	v_div_scale_f32 v6, s[10:11], v143, v143, v5
	v_rcp_f32_e32 v7, v6
	s_nop 0
	v_fma_f32 v8, -v6, v7, 1.0
	v_fmac_f32_e32 v7, v8, v7
	v_div_scale_f32 v8, vcc, v5, v143, v5
	v_mul_f32_e32 v9, v8, v7
	v_fma_f32 v10, -v6, v9, v8
	v_fmac_f32_e32 v9, v10, v7
	v_fma_f32 v6, -v6, v9, v8
	v_div_fmas_f32 v6, v6, v7, v9
	v_div_fixup_f32 v5, v6, v143, v5
	v_lshlrev_b32_e32 v6, 2, v142
	ds_write_b32 v6, v5
	v_cvt_f32_ubyte0_e32 v0, v142
	s_mov_b32 s10, 0xc37f0000
	v_div_scale_f32 v5, s[0:1], s10, s10, v0
	v_rcp_f32_e32 v6, v5
	s_nop 0
	v_fma_f32 v7, -v5, v6, 1.0
	v_fmac_f32_e32 v6, v7, v6
	v_div_scale_f32 v7, vcc, v0, s10, v0
	v_mul_f32_e32 v8, v7, v6
	v_fma_f32 v9, -v5, v8, v7
	v_fmac_f32_e32 v8, v9, v6
	v_fma_f32 v5, -v5, v8, v7
	v_div_fmas_f32 v5, v5, v6, v8
	v_div_fixup_f32 v0, v5, s10, v0
	v_fmamk_f32 v0, v0, 0x41447cbd, v192
	v_and_b32_e32 v121, 0x7fffffff, v0
	v_mov_b32_e32 v122, v121
	s_nop 1
	v_permlane32_swap_b32_e32 v121, v122
	s_waitcnt lgkmcnt(0)
	s_barrier
	ds_read_b128 v[82:85], v118 offset:0
	ds_read_b128 v[86:89], v118 offset:16
	ds_read_b128 v[90:93], v118 offset:32
	ds_read_b128 v[94:97], v118 offset:48
	ds_read_b128 v[98:101], v118 offset:64
	ds_read_b128 v[102:105], v118 offset:80
	ds_read_b128 v[106:109], v118 offset:96
	ds_read_b128 v[110:113], v118 offset:112
	s_waitcnt vmcnt(0)
	s_waitcnt lgkmcnt(7)
	v_mfma_f32_32x32x2_f32 v[154:169], v82, v18, 0
	v_mfma_f32_32x32x2_f32 v[218:233], v82, v50, 0
	v_mfma_f32_32x32x2_f32 v[154:169], v83, v19, v[154:169]
	v_mfma_f32_32x32x2_f32 v[218:233], v83, v51, v[218:233]
	v_mfma_f32_32x32x2_f32 v[154:169], v84, v20, v[154:169]
	v_mfma_f32_32x32x2_f32 v[218:233], v84, v52, v[218:233]
	v_mfma_f32_32x32x2_f32 v[154:169], v85, v21, v[154:169]
	v_mfma_f32_32x32x2_f32 v[218:233], v85, v53, v[218:233]
	s_waitcnt lgkmcnt(6)
	v_mfma_f32_32x32x2_f32 v[154:169], v86, v22, v[154:169]
	v_mfma_f32_32x32x2_f32 v[218:233], v86, v54, v[218:233]
	v_mfma_f32_32x32x2_f32 v[154:169], v87, v23, v[154:169]
	v_mfma_f32_32x32x2_f32 v[218:233], v87, v55, v[218:233]
	v_mfma_f32_32x32x2_f32 v[154:169], v88, v24, v[154:169]
	v_mfma_f32_32x32x2_f32 v[218:233], v88, v56, v[218:233]
	v_mfma_f32_32x32x2_f32 v[154:169], v89, v25, v[154:169]
	v_mfma_f32_32x32x2_f32 v[218:233], v89, v57, v[218:233]
	s_waitcnt lgkmcnt(5)
	v_mfma_f32_32x32x2_f32 v[154:169], v90, v26, v[154:169]
	v_mfma_f32_32x32x2_f32 v[218:233], v90, v58, v[218:233]
	v_mfma_f32_32x32x2_f32 v[154:169], v91, v27, v[154:169]
	v_mfma_f32_32x32x2_f32 v[218:233], v91, v59, v[218:233]
	v_mfma_f32_32x32x2_f32 v[154:169], v92, v28, v[154:169]
	v_mfma_f32_32x32x2_f32 v[218:233], v92, v60, v[218:233]
	v_mfma_f32_32x32x2_f32 v[154:169], v93, v29, v[154:169]
	v_mfma_f32_32x32x2_f32 v[218:233], v93, v61, v[218:233]
	s_waitcnt lgkmcnt(4)
	v_mfma_f32_32x32x2_f32 v[154:169], v94, v30, v[154:169]
	v_mfma_f32_32x32x2_f32 v[218:233], v94, v62, v[218:233]
	v_mfma_f32_32x32x2_f32 v[154:169], v95, v31, v[154:169]
	v_mfma_f32_32x32x2_f32 v[218:233], v95, v63, v[218:233]
	v_mfma_f32_32x32x2_f32 v[154:169], v96, v32, v[154:169]
	v_mfma_f32_32x32x2_f32 v[218:233], v96, v64, v[218:233]
	v_mfma_f32_32x32x2_f32 v[154:169], v97, v33, v[154:169]
	v_mfma_f32_32x32x2_f32 v[218:233], v97, v65, v[218:233]
	s_waitcnt lgkmcnt(3)
	v_mfma_f32_32x32x2_f32 v[154:169], v98, v34, v[154:169]
	v_mfma_f32_32x32x2_f32 v[218:233], v98, v66, v[218:233]
	v_mfma_f32_32x32x2_f32 v[154:169], v99, v35, v[154:169]
	v_mfma_f32_32x32x2_f32 v[218:233], v99, v67, v[218:233]
	v_mfma_f32_32x32x2_f32 v[154:169], v100, v36, v[154:169]
	v_mfma_f32_32x32x2_f32 v[218:233], v100, v68, v[218:233]
	v_mfma_f32_32x32x2_f32 v[154:169], v101, v37, v[154:169]
	v_mfma_f32_32x32x2_f32 v[218:233], v101, v69, v[218:233]
	s_waitcnt lgkmcnt(2)
	v_mfma_f32_32x32x2_f32 v[154:169], v102, v38, v[154:169]
	v_mfma_f32_32x32x2_f32 v[218:233], v102, v70, v[218:233]
	v_mfma_f32_32x32x2_f32 v[154:169], v103, v39, v[154:169]
	v_mfma_f32_32x32x2_f32 v[218:233], v103, v71, v[218:233]
	v_mfma_f32_32x32x2_f32 v[154:169], v104, v40, v[154:169]
	v_mfma_f32_32x32x2_f32 v[218:233], v104, v72, v[218:233]
	v_mfma_f32_32x32x2_f32 v[154:169], v105, v41, v[154:169]
	v_mfma_f32_32x32x2_f32 v[218:233], v105, v73, v[218:233]
	s_waitcnt lgkmcnt(1)
	v_mfma_f32_32x32x2_f32 v[154:169], v106, v42, v[154:169]
	v_mfma_f32_32x32x2_f32 v[218:233], v106, v74, v[218:233]
	v_mfma_f32_32x32x2_f32 v[154:169], v107, v43, v[154:169]
	v_mfma_f32_32x32x2_f32 v[218:233], v107, v75, v[218:233]
	v_mfma_f32_32x32x2_f32 v[154:169], v108, v44, v[154:169]
	v_mfma_f32_32x32x2_f32 v[218:233], v108, v76, v[218:233]
	v_mfma_f32_32x32x2_f32 v[154:169], v109, v45, v[154:169]
	v_mfma_f32_32x32x2_f32 v[218:233], v109, v77, v[218:233]
	s_waitcnt lgkmcnt(0)
	v_mfma_f32_32x32x2_f32 v[154:169], v110, v46, v[154:169]
	v_mfma_f32_32x32x2_f32 v[218:233], v110, v78, v[218:233]
	v_mfma_f32_32x32x2_f32 v[154:169], v111, v47, v[154:169]
	v_mfma_f32_32x32x2_f32 v[218:233], v111, v79, v[218:233]
	v_mfma_f32_32x32x2_f32 v[154:169], v112, v48, v[154:169]
	v_mfma_f32_32x32x2_f32 v[218:233], v112, v80, v[218:233]
	v_mfma_f32_32x32x2_f32 v[154:169], v113, v49, v[154:169]
	v_mfma_f32_32x32x2_f32 v[218:233], v113, v81, v[218:233]
	s_nop 15
	s_nop 15
	ds_read_b128 v[114:117], v119 offset:0
	s_waitcnt lgkmcnt(0)
	v_mul_f32_e32 v124, v121, v114
	v_mul_f32_e32 v125, v121, v115
	v_mul_f32_e32 v126, v121, v116
	v_mul_f32_e32 v127, v121, v117
	v_mul_f32_e32 v128, 0x3fb8aa3b, v124
	v_fma_f32 v129, v124, s96, -v128
	v_rndne_f32_e32 v130, v128
	v_fmac_f32_e32 v129, 0x32a5705f, v124
	v_sub_f32_e32 v128, v128, v130
	v_add_f32_e32 v128, v128, v129
	v_exp_f32_e32 v128, v128
	v_cvt_i32_f32_e32 v129, v130
	v_cmp_ngt_f32_e32 vcc, s68, v124
	v_ldexp_f32 v128, v128, v129
	s_nop 0
	v_cndmask_b32_e32 v128, 0, v128, vcc
	v_cmp_nlt_f32_e32 vcc, s2, v124
	s_nop 1
	v_cndmask_b32_e32 v124, v204, v128, vcc
	v_mul_f32_e32 v128, 0x3fb8aa3b, v125
	v_fma_f32 v129, v125, s96, -v128
	v_rndne_f32_e32 v130, v128
	v_fmac_f32_e32 v129, 0x32a5705f, v125
	v_sub_f32_e32 v128, v128, v130
	v_add_f32_e32 v128, v128, v129
	v_exp_f32_e32 v128, v128
	v_cvt_i32_f32_e32 v129, v130
	v_cmp_ngt_f32_e32 vcc, s68, v125
	v_ldexp_f32 v128, v128, v129
	s_nop 0
	v_cndmask_b32_e32 v128, 0, v128, vcc
	v_cmp_nlt_f32_e32 vcc, s2, v125
	s_nop 1
	v_cndmask_b32_e32 v125, v204, v128, vcc
	v_mul_f32_e32 v128, 0x3fb8aa3b, v126
	v_fma_f32 v129, v126, s96, -v128
	v_rndne_f32_e32 v130, v128
	v_fmac_f32_e32 v129, 0x32a5705f, v126
	v_sub_f32_e32 v128, v128, v130
	v_add_f32_e32 v128, v128, v129
	v_exp_f32_e32 v128, v128
	v_cvt_i32_f32_e32 v129, v130
	v_cmp_ngt_f32_e32 vcc, s68, v126
	v_ldexp_f32 v128, v128, v129
	s_nop 0
	v_cndmask_b32_e32 v128, 0, v128, vcc
	v_cmp_nlt_f32_e32 vcc, s2, v126
	s_nop 1
	v_cndmask_b32_e32 v126, v204, v128, vcc
	v_mul_f32_e32 v128, 0x3fb8aa3b, v127
	v_fma_f32 v129, v127, s96, -v128
	v_rndne_f32_e32 v130, v128
	v_fmac_f32_e32 v129, 0x32a5705f, v127
	v_sub_f32_e32 v128, v128, v130
	v_add_f32_e32 v128, v128, v129
	v_exp_f32_e32 v128, v128
	v_cvt_i32_f32_e32 v129, v130
	v_cmp_ngt_f32_e32 vcc, s68, v127
	v_ldexp_f32 v128, v128, v129
	s_nop 0
	v_cndmask_b32_e32 v128, 0, v128, vcc
	v_cmp_nlt_f32_e32 vcc, s2, v127
	s_nop 1
	v_cndmask_b32_e32 v127, v204, v128, vcc
	v_mul_f32_e32 v124, v124, v154
	v_mul_f32_e32 v125, v125, v155
	v_mul_f32_e32 v126, v126, v156
	v_mul_f32_e32 v127, v127, v157
	v_cvt_pk_bf16_f32 v132, v124, v125
	v_cvt_pk_bf16_f32 v133, v126, v127
	ds_write_b64 v120, v[132:133] offset:0
	v_mul_f32_e32 v124, v122, v114
	v_mul_f32_e32 v125, v122, v115
	v_mul_f32_e32 v126, v122, v116
	v_mul_f32_e32 v127, v122, v117
	v_mul_f32_e32 v128, 0x3fb8aa3b, v124
	v_fma_f32 v129, v124, s96, -v128
	v_rndne_f32_e32 v130, v128
	v_fmac_f32_e32 v129, 0x32a5705f, v124
	v_sub_f32_e32 v128, v128, v130
	v_add_f32_e32 v128, v128, v129
	v_exp_f32_e32 v128, v128
	v_cvt_i32_f32_e32 v129, v130
	v_cmp_ngt_f32_e32 vcc, s68, v124
	v_ldexp_f32 v128, v128, v129
	s_nop 0
	v_cndmask_b32_e32 v128, 0, v128, vcc
	v_cmp_nlt_f32_e32 vcc, s2, v124
	s_nop 1
	v_cndmask_b32_e32 v124, v204, v128, vcc
	v_mul_f32_e32 v128, 0x3fb8aa3b, v125
	v_fma_f32 v129, v125, s96, -v128
	v_rndne_f32_e32 v130, v128
	v_fmac_f32_e32 v129, 0x32a5705f, v125
	v_sub_f32_e32 v128, v128, v130
	v_add_f32_e32 v128, v128, v129
	v_exp_f32_e32 v128, v128
	v_cvt_i32_f32_e32 v129, v130
	v_cmp_ngt_f32_e32 vcc, s68, v125
	v_ldexp_f32 v128, v128, v129
	s_nop 0
	v_cndmask_b32_e32 v128, 0, v128, vcc
	v_cmp_nlt_f32_e32 vcc, s2, v125
	s_nop 1
	v_cndmask_b32_e32 v125, v204, v128, vcc
	v_mul_f32_e32 v128, 0x3fb8aa3b, v126
	v_fma_f32 v129, v126, s96, -v128
	v_rndne_f32_e32 v130, v128
	v_fmac_f32_e32 v129, 0x32a5705f, v126
	v_sub_f32_e32 v128, v128, v130
	v_add_f32_e32 v128, v128, v129
	v_exp_f32_e32 v128, v128
	v_cvt_i32_f32_e32 v129, v130
	v_cmp_ngt_f32_e32 vcc, s68, v126
	v_ldexp_f32 v128, v128, v129
	s_nop 0
	v_cndmask_b32_e32 v128, 0, v128, vcc
	v_cmp_nlt_f32_e32 vcc, s2, v126
	s_nop 1
	v_cndmask_b32_e32 v126, v204, v128, vcc
	v_mul_f32_e32 v128, 0x3fb8aa3b, v127
	v_fma_f32 v129, v127, s96, -v128
	v_rndne_f32_e32 v130, v128
	v_fmac_f32_e32 v129, 0x32a5705f, v127
	v_sub_f32_e32 v128, v128, v130
	v_add_f32_e32 v128, v128, v129
	v_exp_f32_e32 v128, v128
	v_cvt_i32_f32_e32 v129, v130
	v_cmp_ngt_f32_e32 vcc, s68, v127
	v_ldexp_f32 v128, v128, v129
	s_nop 0
	v_cndmask_b32_e32 v128, 0, v128, vcc
	v_cmp_nlt_f32_e32 vcc, s2, v127
	s_nop 1
	v_cndmask_b32_e32 v127, v204, v128, vcc
	v_mul_f32_e32 v124, v124, v218
	v_mul_f32_e32 v125, v125, v219
	v_mul_f32_e32 v126, v126, v220
	v_mul_f32_e32 v127, v127, v221
	v_cvt_pk_bf16_f32 v132, v124, v125
	v_cvt_pk_bf16_f32 v133, v126, v127
	ds_write_b64 v120, v[132:133] offset:4608
	ds_read_b128 v[114:117], v119 offset:32
	s_waitcnt lgkmcnt(0)
	v_mul_f32_e32 v124, v121, v114
	v_mul_f32_e32 v125, v121, v115
	v_mul_f32_e32 v126, v121, v116
	v_mul_f32_e32 v127, v121, v117
	v_mul_f32_e32 v128, 0x3fb8aa3b, v124
	v_fma_f32 v129, v124, s96, -v128
	v_rndne_f32_e32 v130, v128
	v_fmac_f32_e32 v129, 0x32a5705f, v124
	v_sub_f32_e32 v128, v128, v130
	v_add_f32_e32 v128, v128, v129
	v_exp_f32_e32 v128, v128
	v_cvt_i32_f32_e32 v129, v130
	v_cmp_ngt_f32_e32 vcc, s68, v124
	v_ldexp_f32 v128, v128, v129
	s_nop 0
	v_cndmask_b32_e32 v128, 0, v128, vcc
	v_cmp_nlt_f32_e32 vcc, s2, v124
	s_nop 1
	v_cndmask_b32_e32 v124, v204, v128, vcc
	v_mul_f32_e32 v128, 0x3fb8aa3b, v125
	v_fma_f32 v129, v125, s96, -v128
	v_rndne_f32_e32 v130, v128
	v_fmac_f32_e32 v129, 0x32a5705f, v125
	v_sub_f32_e32 v128, v128, v130
	v_add_f32_e32 v128, v128, v129
	v_exp_f32_e32 v128, v128
	v_cvt_i32_f32_e32 v129, v130
	v_cmp_ngt_f32_e32 vcc, s68, v125
	v_ldexp_f32 v128, v128, v129
	s_nop 0
	v_cndmask_b32_e32 v128, 0, v128, vcc
	v_cmp_nlt_f32_e32 vcc, s2, v125
	s_nop 1
	v_cndmask_b32_e32 v125, v204, v128, vcc
	v_mul_f32_e32 v128, 0x3fb8aa3b, v126
	v_fma_f32 v129, v126, s96, -v128
	v_rndne_f32_e32 v130, v128
	v_fmac_f32_e32 v129, 0x32a5705f, v126
	v_sub_f32_e32 v128, v128, v130
	v_add_f32_e32 v128, v128, v129
	v_exp_f32_e32 v128, v128
	v_cvt_i32_f32_e32 v129, v130
	v_cmp_ngt_f32_e32 vcc, s68, v126
	v_ldexp_f32 v128, v128, v129
	s_nop 0
	v_cndmask_b32_e32 v128, 0, v128, vcc
	v_cmp_nlt_f32_e32 vcc, s2, v126
	s_nop 1
	v_cndmask_b32_e32 v126, v204, v128, vcc
	v_mul_f32_e32 v128, 0x3fb8aa3b, v127
	v_fma_f32 v129, v127, s96, -v128
	v_rndne_f32_e32 v130, v128
	v_fmac_f32_e32 v129, 0x32a5705f, v127
	v_sub_f32_e32 v128, v128, v130
	v_add_f32_e32 v128, v128, v129
	v_exp_f32_e32 v128, v128
	v_cvt_i32_f32_e32 v129, v130
	v_cmp_ngt_f32_e32 vcc, s68, v127
	v_ldexp_f32 v128, v128, v129
	s_nop 0
	v_cndmask_b32_e32 v128, 0, v128, vcc
	v_cmp_nlt_f32_e32 vcc, s2, v127
	s_nop 1
	v_cndmask_b32_e32 v127, v204, v128, vcc
	v_mul_f32_e32 v124, v124, v158
	v_mul_f32_e32 v125, v125, v159
	v_mul_f32_e32 v126, v126, v160
	v_mul_f32_e32 v127, v127, v161
	v_cvt_pk_bf16_f32 v132, v124, v125
	v_cvt_pk_bf16_f32 v133, v126, v127
	ds_write_b64 v120, v[132:133] offset:16
	v_mul_f32_e32 v124, v122, v114
	v_mul_f32_e32 v125, v122, v115
	v_mul_f32_e32 v126, v122, v116
	v_mul_f32_e32 v127, v122, v117
	v_mul_f32_e32 v128, 0x3fb8aa3b, v124
	v_fma_f32 v129, v124, s96, -v128
	v_rndne_f32_e32 v130, v128
	v_fmac_f32_e32 v129, 0x32a5705f, v124
	v_sub_f32_e32 v128, v128, v130
	v_add_f32_e32 v128, v128, v129
	v_exp_f32_e32 v128, v128
	v_cvt_i32_f32_e32 v129, v130
	v_cmp_ngt_f32_e32 vcc, s68, v124
	v_ldexp_f32 v128, v128, v129
	s_nop 0
	v_cndmask_b32_e32 v128, 0, v128, vcc
	v_cmp_nlt_f32_e32 vcc, s2, v124
	s_nop 1
	v_cndmask_b32_e32 v124, v204, v128, vcc
	v_mul_f32_e32 v128, 0x3fb8aa3b, v125
	v_fma_f32 v129, v125, s96, -v128
	v_rndne_f32_e32 v130, v128
	v_fmac_f32_e32 v129, 0x32a5705f, v125
	v_sub_f32_e32 v128, v128, v130
	v_add_f32_e32 v128, v128, v129
	v_exp_f32_e32 v128, v128
	v_cvt_i32_f32_e32 v129, v130
	v_cmp_ngt_f32_e32 vcc, s68, v125
	v_ldexp_f32 v128, v128, v129
	s_nop 0
	v_cndmask_b32_e32 v128, 0, v128, vcc
	v_cmp_nlt_f32_e32 vcc, s2, v125
	s_nop 1
	v_cndmask_b32_e32 v125, v204, v128, vcc
	v_mul_f32_e32 v128, 0x3fb8aa3b, v126
	v_fma_f32 v129, v126, s96, -v128
	v_rndne_f32_e32 v130, v128
	v_fmac_f32_e32 v129, 0x32a5705f, v126
	v_sub_f32_e32 v128, v128, v130
	v_add_f32_e32 v128, v128, v129
	v_exp_f32_e32 v128, v128
	v_cvt_i32_f32_e32 v129, v130
	v_cmp_ngt_f32_e32 vcc, s68, v126
	v_ldexp_f32 v128, v128, v129
	s_nop 0
	v_cndmask_b32_e32 v128, 0, v128, vcc
	v_cmp_nlt_f32_e32 vcc, s2, v126
	s_nop 1
	v_cndmask_b32_e32 v126, v204, v128, vcc
	v_mul_f32_e32 v128, 0x3fb8aa3b, v127
	v_fma_f32 v129, v127, s96, -v128
	v_rndne_f32_e32 v130, v128
	v_fmac_f32_e32 v129, 0x32a5705f, v127
	v_sub_f32_e32 v128, v128, v130
	v_add_f32_e32 v128, v128, v129
	v_exp_f32_e32 v128, v128
	v_cvt_i32_f32_e32 v129, v130
	v_cmp_ngt_f32_e32 vcc, s68, v127
	v_ldexp_f32 v128, v128, v129
	s_nop 0
	v_cndmask_b32_e32 v128, 0, v128, vcc
	v_cmp_nlt_f32_e32 vcc, s2, v127
	s_nop 1
	v_cndmask_b32_e32 v127, v204, v128, vcc
	v_mul_f32_e32 v124, v124, v222
	v_mul_f32_e32 v125, v125, v223
	v_mul_f32_e32 v126, v126, v224
	v_mul_f32_e32 v127, v127, v225
	v_cvt_pk_bf16_f32 v132, v124, v125
	v_cvt_pk_bf16_f32 v133, v126, v127
	ds_write_b64 v120, v[132:133] offset:4624
	ds_read_b128 v[114:117], v119 offset:64
	s_waitcnt lgkmcnt(0)
	v_mul_f32_e32 v124, v121, v114
	v_mul_f32_e32 v125, v121, v115
	v_mul_f32_e32 v126, v121, v116
	v_mul_f32_e32 v127, v121, v117
	v_mul_f32_e32 v128, 0x3fb8aa3b, v124
	v_fma_f32 v129, v124, s96, -v128
	v_rndne_f32_e32 v130, v128
	v_fmac_f32_e32 v129, 0x32a5705f, v124
	v_sub_f32_e32 v128, v128, v130
	v_add_f32_e32 v128, v128, v129
	v_exp_f32_e32 v128, v128
	v_cvt_i32_f32_e32 v129, v130
	v_cmp_ngt_f32_e32 vcc, s68, v124
	v_ldexp_f32 v128, v128, v129
	s_nop 0
	v_cndmask_b32_e32 v128, 0, v128, vcc
	v_cmp_nlt_f32_e32 vcc, s2, v124
	s_nop 1
	v_cndmask_b32_e32 v124, v204, v128, vcc
	v_mul_f32_e32 v128, 0x3fb8aa3b, v125
	v_fma_f32 v129, v125, s96, -v128
	v_rndne_f32_e32 v130, v128
	v_fmac_f32_e32 v129, 0x32a5705f, v125
	v_sub_f32_e32 v128, v128, v130
	v_add_f32_e32 v128, v128, v129
	v_exp_f32_e32 v128, v128
	v_cvt_i32_f32_e32 v129, v130
	v_cmp_ngt_f32_e32 vcc, s68, v125
	v_ldexp_f32 v128, v128, v129
	s_nop 0
	v_cndmask_b32_e32 v128, 0, v128, vcc
	v_cmp_nlt_f32_e32 vcc, s2, v125
	s_nop 1
	v_cndmask_b32_e32 v125, v204, v128, vcc
	v_mul_f32_e32 v128, 0x3fb8aa3b, v126
	v_fma_f32 v129, v126, s96, -v128
	v_rndne_f32_e32 v130, v128
	v_fmac_f32_e32 v129, 0x32a5705f, v126
	v_sub_f32_e32 v128, v128, v130
	v_add_f32_e32 v128, v128, v129
	v_exp_f32_e32 v128, v128
	v_cvt_i32_f32_e32 v129, v130
	v_cmp_ngt_f32_e32 vcc, s68, v126
	v_ldexp_f32 v128, v128, v129
	s_nop 0
	v_cndmask_b32_e32 v128, 0, v128, vcc
	v_cmp_nlt_f32_e32 vcc, s2, v126
	s_nop 1
	v_cndmask_b32_e32 v126, v204, v128, vcc
	v_mul_f32_e32 v128, 0x3fb8aa3b, v127
	v_fma_f32 v129, v127, s96, -v128
	v_rndne_f32_e32 v130, v128
	v_fmac_f32_e32 v129, 0x32a5705f, v127
	v_sub_f32_e32 v128, v128, v130
	v_add_f32_e32 v128, v128, v129
	v_exp_f32_e32 v128, v128
	v_cvt_i32_f32_e32 v129, v130
	v_cmp_ngt_f32_e32 vcc, s68, v127
	v_ldexp_f32 v128, v128, v129
	s_nop 0
	v_cndmask_b32_e32 v128, 0, v128, vcc
	v_cmp_nlt_f32_e32 vcc, s2, v127
	s_nop 1
	v_cndmask_b32_e32 v127, v204, v128, vcc
	v_mul_f32_e32 v124, v124, v162
	v_mul_f32_e32 v125, v125, v163
	v_mul_f32_e32 v126, v126, v164
	v_mul_f32_e32 v127, v127, v165
	v_cvt_pk_bf16_f32 v132, v124, v125
	v_cvt_pk_bf16_f32 v133, v126, v127
	ds_write_b64 v120, v[132:133] offset:32
	v_mul_f32_e32 v124, v122, v114
	v_mul_f32_e32 v125, v122, v115
	v_mul_f32_e32 v126, v122, v116
	v_mul_f32_e32 v127, v122, v117
	v_mul_f32_e32 v128, 0x3fb8aa3b, v124
	v_fma_f32 v129, v124, s96, -v128
	v_rndne_f32_e32 v130, v128
	v_fmac_f32_e32 v129, 0x32a5705f, v124
	v_sub_f32_e32 v128, v128, v130
	v_add_f32_e32 v128, v128, v129
	v_exp_f32_e32 v128, v128
	v_cvt_i32_f32_e32 v129, v130
	v_cmp_ngt_f32_e32 vcc, s68, v124
	v_ldexp_f32 v128, v128, v129
	s_nop 0
	v_cndmask_b32_e32 v128, 0, v128, vcc
	v_cmp_nlt_f32_e32 vcc, s2, v124
	s_nop 1
	v_cndmask_b32_e32 v124, v204, v128, vcc
	v_mul_f32_e32 v128, 0x3fb8aa3b, v125
	v_fma_f32 v129, v125, s96, -v128
	v_rndne_f32_e32 v130, v128
	v_fmac_f32_e32 v129, 0x32a5705f, v125
	v_sub_f32_e32 v128, v128, v130
	v_add_f32_e32 v128, v128, v129
	v_exp_f32_e32 v128, v128
	v_cvt_i32_f32_e32 v129, v130
	v_cmp_ngt_f32_e32 vcc, s68, v125
	v_ldexp_f32 v128, v128, v129
	s_nop 0
	v_cndmask_b32_e32 v128, 0, v128, vcc
	v_cmp_nlt_f32_e32 vcc, s2, v125
	s_nop 1
	v_cndmask_b32_e32 v125, v204, v128, vcc
	v_mul_f32_e32 v128, 0x3fb8aa3b, v126
	v_fma_f32 v129, v126, s96, -v128
	v_rndne_f32_e32 v130, v128
	v_fmac_f32_e32 v129, 0x32a5705f, v126
	v_sub_f32_e32 v128, v128, v130
	v_add_f32_e32 v128, v128, v129
	v_exp_f32_e32 v128, v128
	v_cvt_i32_f32_e32 v129, v130
	v_cmp_ngt_f32_e32 vcc, s68, v126
	v_ldexp_f32 v128, v128, v129
	s_nop 0
	v_cndmask_b32_e32 v128, 0, v128, vcc
	v_cmp_nlt_f32_e32 vcc, s2, v126
	s_nop 1
	v_cndmask_b32_e32 v126, v204, v128, vcc
	v_mul_f32_e32 v128, 0x3fb8aa3b, v127
	v_fma_f32 v129, v127, s96, -v128
	v_rndne_f32_e32 v130, v128
	v_fmac_f32_e32 v129, 0x32a5705f, v127
	v_sub_f32_e32 v128, v128, v130
	v_add_f32_e32 v128, v128, v129
	v_exp_f32_e32 v128, v128
	v_cvt_i32_f32_e32 v129, v130
	v_cmp_ngt_f32_e32 vcc, s68, v127
	v_ldexp_f32 v128, v128, v129
	s_nop 0
	v_cndmask_b32_e32 v128, 0, v128, vcc
	v_cmp_nlt_f32_e32 vcc, s2, v127
	s_nop 1
	v_cndmask_b32_e32 v127, v204, v128, vcc
	v_mul_f32_e32 v124, v124, v226
	v_mul_f32_e32 v125, v125, v227
	v_mul_f32_e32 v126, v126, v228
	v_mul_f32_e32 v127, v127, v229
	v_cvt_pk_bf16_f32 v132, v124, v125
	v_cvt_pk_bf16_f32 v133, v126, v127
	ds_write_b64 v120, v[132:133] offset:4640
	ds_read_b128 v[114:117], v119 offset:96
	s_waitcnt lgkmcnt(0)
	v_mul_f32_e32 v124, v121, v114
	v_mul_f32_e32 v125, v121, v115
	v_mul_f32_e32 v126, v121, v116
	v_mul_f32_e32 v127, v121, v117
	v_mul_f32_e32 v128, 0x3fb8aa3b, v124
	v_fma_f32 v129, v124, s96, -v128
	v_rndne_f32_e32 v130, v128
	v_fmac_f32_e32 v129, 0x32a5705f, v124
	v_sub_f32_e32 v128, v128, v130
	v_add_f32_e32 v128, v128, v129
	v_exp_f32_e32 v128, v128
	v_cvt_i32_f32_e32 v129, v130
	v_cmp_ngt_f32_e32 vcc, s68, v124
	v_ldexp_f32 v128, v128, v129
	s_nop 0
	v_cndmask_b32_e32 v128, 0, v128, vcc
	v_cmp_nlt_f32_e32 vcc, s2, v124
	s_nop 1
	v_cndmask_b32_e32 v124, v204, v128, vcc
	v_mul_f32_e32 v128, 0x3fb8aa3b, v125
	v_fma_f32 v129, v125, s96, -v128
	v_rndne_f32_e32 v130, v128
	v_fmac_f32_e32 v129, 0x32a5705f, v125
	v_sub_f32_e32 v128, v128, v130
	v_add_f32_e32 v128, v128, v129
	v_exp_f32_e32 v128, v128
	v_cvt_i32_f32_e32 v129, v130
	v_cmp_ngt_f32_e32 vcc, s68, v125
	v_ldexp_f32 v128, v128, v129
	s_nop 0
	v_cndmask_b32_e32 v128, 0, v128, vcc
	v_cmp_nlt_f32_e32 vcc, s2, v125
	s_nop 1
	v_cndmask_b32_e32 v125, v204, v128, vcc
	v_mul_f32_e32 v128, 0x3fb8aa3b, v126
	v_fma_f32 v129, v126, s96, -v128
	v_rndne_f32_e32 v130, v128
	v_fmac_f32_e32 v129, 0x32a5705f, v126
	v_sub_f32_e32 v128, v128, v130
	v_add_f32_e32 v128, v128, v129
	v_exp_f32_e32 v128, v128
	v_cvt_i32_f32_e32 v129, v130
	v_cmp_ngt_f32_e32 vcc, s68, v126
	v_ldexp_f32 v128, v128, v129
	s_nop 0
	v_cndmask_b32_e32 v128, 0, v128, vcc
	v_cmp_nlt_f32_e32 vcc, s2, v126
	s_nop 1
	v_cndmask_b32_e32 v126, v204, v128, vcc
	v_mul_f32_e32 v128, 0x3fb8aa3b, v127
	v_fma_f32 v129, v127, s96, -v128
	v_rndne_f32_e32 v130, v128
	v_fmac_f32_e32 v129, 0x32a5705f, v127
	v_sub_f32_e32 v128, v128, v130
	v_add_f32_e32 v128, v128, v129
	v_exp_f32_e32 v128, v128
	v_cvt_i32_f32_e32 v129, v130
	v_cmp_ngt_f32_e32 vcc, s68, v127
	v_ldexp_f32 v128, v128, v129
	s_nop 0
	v_cndmask_b32_e32 v128, 0, v128, vcc
	v_cmp_nlt_f32_e32 vcc, s2, v127
	s_nop 1
	v_cndmask_b32_e32 v127, v204, v128, vcc
	v_mul_f32_e32 v124, v124, v166
	v_mul_f32_e32 v125, v125, v167
	v_mul_f32_e32 v126, v126, v168
	v_mul_f32_e32 v127, v127, v169
	v_cvt_pk_bf16_f32 v132, v124, v125
	v_cvt_pk_bf16_f32 v133, v126, v127
	ds_write_b64 v120, v[132:133] offset:48
	v_mul_f32_e32 v124, v122, v114
	v_mul_f32_e32 v125, v122, v115
	v_mul_f32_e32 v126, v122, v116
	v_mul_f32_e32 v127, v122, v117
	v_mul_f32_e32 v128, 0x3fb8aa3b, v124
	v_fma_f32 v129, v124, s96, -v128
	v_rndne_f32_e32 v130, v128
	v_fmac_f32_e32 v129, 0x32a5705f, v124
	v_sub_f32_e32 v128, v128, v130
	v_add_f32_e32 v128, v128, v129
	v_exp_f32_e32 v128, v128
	v_cvt_i32_f32_e32 v129, v130
	v_cmp_ngt_f32_e32 vcc, s68, v124
	v_ldexp_f32 v128, v128, v129
	s_nop 0
	v_cndmask_b32_e32 v128, 0, v128, vcc
	v_cmp_nlt_f32_e32 vcc, s2, v124
	s_nop 1
	v_cndmask_b32_e32 v124, v204, v128, vcc
	v_mul_f32_e32 v128, 0x3fb8aa3b, v125
	v_fma_f32 v129, v125, s96, -v128
	v_rndne_f32_e32 v130, v128
	v_fmac_f32_e32 v129, 0x32a5705f, v125
	v_sub_f32_e32 v128, v128, v130
	v_add_f32_e32 v128, v128, v129
	v_exp_f32_e32 v128, v128
	v_cvt_i32_f32_e32 v129, v130
	v_cmp_ngt_f32_e32 vcc, s68, v125
	v_ldexp_f32 v128, v128, v129
	s_nop 0
	v_cndmask_b32_e32 v128, 0, v128, vcc
	v_cmp_nlt_f32_e32 vcc, s2, v125
	s_nop 1
	v_cndmask_b32_e32 v125, v204, v128, vcc
	v_mul_f32_e32 v128, 0x3fb8aa3b, v126
	v_fma_f32 v129, v126, s96, -v128
	v_rndne_f32_e32 v130, v128
	v_fmac_f32_e32 v129, 0x32a5705f, v126
	v_sub_f32_e32 v128, v128, v130
	v_add_f32_e32 v128, v128, v129
	v_exp_f32_e32 v128, v128
	v_cvt_i32_f32_e32 v129, v130
	v_cmp_ngt_f32_e32 vcc, s68, v126
	v_ldexp_f32 v128, v128, v129
	s_nop 0
	v_cndmask_b32_e32 v128, 0, v128, vcc
	v_cmp_nlt_f32_e32 vcc, s2, v126
	s_nop 1
	v_cndmask_b32_e32 v126, v204, v128, vcc
	v_mul_f32_e32 v128, 0x3fb8aa3b, v127
	v_fma_f32 v129, v127, s96, -v128
	v_rndne_f32_e32 v130, v128
	v_fmac_f32_e32 v129, 0x32a5705f, v127
	v_sub_f32_e32 v128, v128, v130
	v_add_f32_e32 v128, v128, v129
	v_exp_f32_e32 v128, v128
	v_cvt_i32_f32_e32 v129, v130
	v_cmp_ngt_f32_e32 vcc, s68, v127
	v_ldexp_f32 v128, v128, v129
	s_nop 0
	v_cndmask_b32_e32 v128, 0, v128, vcc
	v_cmp_nlt_f32_e32 vcc, s2, v127
	s_nop 1
	v_cndmask_b32_e32 v127, v204, v128, vcc
	v_mul_f32_e32 v124, v124, v230
	v_mul_f32_e32 v125, v125, v231
	v_mul_f32_e32 v126, v126, v232
	v_mul_f32_e32 v127, v127, v233
	v_cvt_pk_bf16_f32 v132, v124, v125
	v_cvt_pk_bf16_f32 v133, v126, v127
	ds_write_b64 v120, v[132:133] offset:4656
	ds_read_b128 v[82:85], v118 offset:8192
	ds_read_b128 v[86:89], v118 offset:8208
	ds_read_b128 v[90:93], v118 offset:8224
	ds_read_b128 v[94:97], v118 offset:8240
	ds_read_b128 v[98:101], v118 offset:8256
	ds_read_b128 v[102:105], v118 offset:8272
	ds_read_b128 v[106:109], v118 offset:8288
	ds_read_b128 v[110:113], v118 offset:8304
	s_waitcnt lgkmcnt(7)
	v_mfma_f32_32x32x2_f32 v[154:169], v82, v18, 0
	v_mfma_f32_32x32x2_f32 v[218:233], v82, v50, 0
	v_mfma_f32_32x32x2_f32 v[154:169], v83, v19, v[154:169]
	v_mfma_f32_32x32x2_f32 v[218:233], v83, v51, v[218:233]
	v_mfma_f32_32x32x2_f32 v[154:169], v84, v20, v[154:169]
	v_mfma_f32_32x32x2_f32 v[218:233], v84, v52, v[218:233]
	v_mfma_f32_32x32x2_f32 v[154:169], v85, v21, v[154:169]
	v_mfma_f32_32x32x2_f32 v[218:233], v85, v53, v[218:233]
	s_waitcnt lgkmcnt(6)
	v_mfma_f32_32x32x2_f32 v[154:169], v86, v22, v[154:169]
	v_mfma_f32_32x32x2_f32 v[218:233], v86, v54, v[218:233]
	v_mfma_f32_32x32x2_f32 v[154:169], v87, v23, v[154:169]
	v_mfma_f32_32x32x2_f32 v[218:233], v87, v55, v[218:233]
	v_mfma_f32_32x32x2_f32 v[154:169], v88, v24, v[154:169]
	v_mfma_f32_32x32x2_f32 v[218:233], v88, v56, v[218:233]
	v_mfma_f32_32x32x2_f32 v[154:169], v89, v25, v[154:169]
	v_mfma_f32_32x32x2_f32 v[218:233], v89, v57, v[218:233]
	s_waitcnt lgkmcnt(5)
	v_mfma_f32_32x32x2_f32 v[154:169], v90, v26, v[154:169]
	v_mfma_f32_32x32x2_f32 v[218:233], v90, v58, v[218:233]
	v_mfma_f32_32x32x2_f32 v[154:169], v91, v27, v[154:169]
	v_mfma_f32_32x32x2_f32 v[218:233], v91, v59, v[218:233]
	v_mfma_f32_32x32x2_f32 v[154:169], v92, v28, v[154:169]
	v_mfma_f32_32x32x2_f32 v[218:233], v92, v60, v[218:233]
	v_mfma_f32_32x32x2_f32 v[154:169], v93, v29, v[154:169]
	v_mfma_f32_32x32x2_f32 v[218:233], v93, v61, v[218:233]
	s_waitcnt lgkmcnt(4)
	v_mfma_f32_32x32x2_f32 v[154:169], v94, v30, v[154:169]
	v_mfma_f32_32x32x2_f32 v[218:233], v94, v62, v[218:233]
	v_mfma_f32_32x32x2_f32 v[154:169], v95, v31, v[154:169]
	v_mfma_f32_32x32x2_f32 v[218:233], v95, v63, v[218:233]
	v_mfma_f32_32x32x2_f32 v[154:169], v96, v32, v[154:169]
	v_mfma_f32_32x32x2_f32 v[218:233], v96, v64, v[218:233]
	v_mfma_f32_32x32x2_f32 v[154:169], v97, v33, v[154:169]
	v_mfma_f32_32x32x2_f32 v[218:233], v97, v65, v[218:233]
	s_waitcnt lgkmcnt(3)
	v_mfma_f32_32x32x2_f32 v[154:169], v98, v34, v[154:169]
	v_mfma_f32_32x32x2_f32 v[218:233], v98, v66, v[218:233]
	v_mfma_f32_32x32x2_f32 v[154:169], v99, v35, v[154:169]
	v_mfma_f32_32x32x2_f32 v[218:233], v99, v67, v[218:233]
	v_mfma_f32_32x32x2_f32 v[154:169], v100, v36, v[154:169]
	v_mfma_f32_32x32x2_f32 v[218:233], v100, v68, v[218:233]
	v_mfma_f32_32x32x2_f32 v[154:169], v101, v37, v[154:169]
	v_mfma_f32_32x32x2_f32 v[218:233], v101, v69, v[218:233]
	s_waitcnt lgkmcnt(2)
	v_mfma_f32_32x32x2_f32 v[154:169], v102, v38, v[154:169]
	v_mfma_f32_32x32x2_f32 v[218:233], v102, v70, v[218:233]
	v_mfma_f32_32x32x2_f32 v[154:169], v103, v39, v[154:169]
	v_mfma_f32_32x32x2_f32 v[218:233], v103, v71, v[218:233]
	v_mfma_f32_32x32x2_f32 v[154:169], v104, v40, v[154:169]
	v_mfma_f32_32x32x2_f32 v[218:233], v104, v72, v[218:233]
	v_mfma_f32_32x32x2_f32 v[154:169], v105, v41, v[154:169]
	v_mfma_f32_32x32x2_f32 v[218:233], v105, v73, v[218:233]
	s_waitcnt lgkmcnt(1)
	v_mfma_f32_32x32x2_f32 v[154:169], v106, v42, v[154:169]
	v_mfma_f32_32x32x2_f32 v[218:233], v106, v74, v[218:233]
	v_mfma_f32_32x32x2_f32 v[154:169], v107, v43, v[154:169]
	v_mfma_f32_32x32x2_f32 v[218:233], v107, v75, v[218:233]
	v_mfma_f32_32x32x2_f32 v[154:169], v108, v44, v[154:169]
	v_mfma_f32_32x32x2_f32 v[218:233], v108, v76, v[218:233]
	v_mfma_f32_32x32x2_f32 v[154:169], v109, v45, v[154:169]
	v_mfma_f32_32x32x2_f32 v[218:233], v109, v77, v[218:233]
	s_waitcnt lgkmcnt(0)
	v_mfma_f32_32x32x2_f32 v[154:169], v110, v46, v[154:169]
	v_mfma_f32_32x32x2_f32 v[218:233], v110, v78, v[218:233]
	v_mfma_f32_32x32x2_f32 v[154:169], v111, v47, v[154:169]
	v_mfma_f32_32x32x2_f32 v[218:233], v111, v79, v[218:233]
	v_mfma_f32_32x32x2_f32 v[154:169], v112, v48, v[154:169]
	v_mfma_f32_32x32x2_f32 v[218:233], v112, v80, v[218:233]
	v_mfma_f32_32x32x2_f32 v[154:169], v113, v49, v[154:169]
	v_mfma_f32_32x32x2_f32 v[218:233], v113, v81, v[218:233]
	s_nop 15
	s_nop 15
	ds_read_b128 v[114:117], v119 offset:128
	s_waitcnt lgkmcnt(0)
	v_mul_f32_e32 v124, v121, v114
	v_mul_f32_e32 v125, v121, v115
	v_mul_f32_e32 v126, v121, v116
	v_mul_f32_e32 v127, v121, v117
	v_mul_f32_e32 v128, 0x3fb8aa3b, v124
	v_fma_f32 v129, v124, s96, -v128
	v_rndne_f32_e32 v130, v128
	v_fmac_f32_e32 v129, 0x32a5705f, v124
	v_sub_f32_e32 v128, v128, v130
	v_add_f32_e32 v128, v128, v129
	v_exp_f32_e32 v128, v128
	v_cvt_i32_f32_e32 v129, v130
	v_cmp_ngt_f32_e32 vcc, s68, v124
	v_ldexp_f32 v128, v128, v129
	s_nop 0
	v_cndmask_b32_e32 v128, 0, v128, vcc
	v_cmp_nlt_f32_e32 vcc, s2, v124
	s_nop 1
	v_cndmask_b32_e32 v124, v204, v128, vcc
	v_mul_f32_e32 v128, 0x3fb8aa3b, v125
	v_fma_f32 v129, v125, s96, -v128
	v_rndne_f32_e32 v130, v128
	v_fmac_f32_e32 v129, 0x32a5705f, v125
	v_sub_f32_e32 v128, v128, v130
	v_add_f32_e32 v128, v128, v129
	v_exp_f32_e32 v128, v128
	v_cvt_i32_f32_e32 v129, v130
	v_cmp_ngt_f32_e32 vcc, s68, v125
	v_ldexp_f32 v128, v128, v129
	s_nop 0
	v_cndmask_b32_e32 v128, 0, v128, vcc
	v_cmp_nlt_f32_e32 vcc, s2, v125
	s_nop 1
	v_cndmask_b32_e32 v125, v204, v128, vcc
	v_mul_f32_e32 v128, 0x3fb8aa3b, v126
	v_fma_f32 v129, v126, s96, -v128
	v_rndne_f32_e32 v130, v128
	v_fmac_f32_e32 v129, 0x32a5705f, v126
	v_sub_f32_e32 v128, v128, v130
	v_add_f32_e32 v128, v128, v129
	v_exp_f32_e32 v128, v128
	v_cvt_i32_f32_e32 v129, v130
	v_cmp_ngt_f32_e32 vcc, s68, v126
	v_ldexp_f32 v128, v128, v129
	s_nop 0
	v_cndmask_b32_e32 v128, 0, v128, vcc
	v_cmp_nlt_f32_e32 vcc, s2, v126
	s_nop 1
	v_cndmask_b32_e32 v126, v204, v128, vcc
	v_mul_f32_e32 v128, 0x3fb8aa3b, v127
	v_fma_f32 v129, v127, s96, -v128
	v_rndne_f32_e32 v130, v128
	v_fmac_f32_e32 v129, 0x32a5705f, v127
	v_sub_f32_e32 v128, v128, v130
	v_add_f32_e32 v128, v128, v129
	v_exp_f32_e32 v128, v128
	v_cvt_i32_f32_e32 v129, v130
	v_cmp_ngt_f32_e32 vcc, s68, v127
	v_ldexp_f32 v128, v128, v129
	s_nop 0
	v_cndmask_b32_e32 v128, 0, v128, vcc
	v_cmp_nlt_f32_e32 vcc, s2, v127
	s_nop 1
	v_cndmask_b32_e32 v127, v204, v128, vcc
	v_mul_f32_e32 v124, v124, v154
	v_mul_f32_e32 v125, v125, v155
	v_mul_f32_e32 v126, v126, v156
	v_mul_f32_e32 v127, v127, v157
	v_cvt_pk_bf16_f32 v132, v124, v125
	v_cvt_pk_bf16_f32 v133, v126, v127
	ds_write_b64 v120, v[132:133] offset:64
	v_mul_f32_e32 v124, v122, v114
	v_mul_f32_e32 v125, v122, v115
	v_mul_f32_e32 v126, v122, v116
	v_mul_f32_e32 v127, v122, v117
	v_mul_f32_e32 v128, 0x3fb8aa3b, v124
	v_fma_f32 v129, v124, s96, -v128
	v_rndne_f32_e32 v130, v128
	v_fmac_f32_e32 v129, 0x32a5705f, v124
	v_sub_f32_e32 v128, v128, v130
	v_add_f32_e32 v128, v128, v129
	v_exp_f32_e32 v128, v128
	v_cvt_i32_f32_e32 v129, v130
	v_cmp_ngt_f32_e32 vcc, s68, v124
	v_ldexp_f32 v128, v128, v129
	s_nop 0
	v_cndmask_b32_e32 v128, 0, v128, vcc
	v_cmp_nlt_f32_e32 vcc, s2, v124
	s_nop 1
	v_cndmask_b32_e32 v124, v204, v128, vcc
	v_mul_f32_e32 v128, 0x3fb8aa3b, v125
	v_fma_f32 v129, v125, s96, -v128
	v_rndne_f32_e32 v130, v128
	v_fmac_f32_e32 v129, 0x32a5705f, v125
	v_sub_f32_e32 v128, v128, v130
	v_add_f32_e32 v128, v128, v129
	v_exp_f32_e32 v128, v128
	v_cvt_i32_f32_e32 v129, v130
	v_cmp_ngt_f32_e32 vcc, s68, v125
	v_ldexp_f32 v128, v128, v129
	s_nop 0
	v_cndmask_b32_e32 v128, 0, v128, vcc
	v_cmp_nlt_f32_e32 vcc, s2, v125
	s_nop 1
	v_cndmask_b32_e32 v125, v204, v128, vcc
	v_mul_f32_e32 v128, 0x3fb8aa3b, v126
	v_fma_f32 v129, v126, s96, -v128
	v_rndne_f32_e32 v130, v128
	v_fmac_f32_e32 v129, 0x32a5705f, v126
	v_sub_f32_e32 v128, v128, v130
	v_add_f32_e32 v128, v128, v129
	v_exp_f32_e32 v128, v128
	v_cvt_i32_f32_e32 v129, v130
	v_cmp_ngt_f32_e32 vcc, s68, v126
	v_ldexp_f32 v128, v128, v129
	s_nop 0
	v_cndmask_b32_e32 v128, 0, v128, vcc
	v_cmp_nlt_f32_e32 vcc, s2, v126
	s_nop 1
	v_cndmask_b32_e32 v126, v204, v128, vcc
	v_mul_f32_e32 v128, 0x3fb8aa3b, v127
	v_fma_f32 v129, v127, s96, -v128
	v_rndne_f32_e32 v130, v128
	v_fmac_f32_e32 v129, 0x32a5705f, v127
	v_sub_f32_e32 v128, v128, v130
	v_add_f32_e32 v128, v128, v129
	v_exp_f32_e32 v128, v128
	v_cvt_i32_f32_e32 v129, v130
	v_cmp_ngt_f32_e32 vcc, s68, v127
	v_ldexp_f32 v128, v128, v129
	s_nop 0
	v_cndmask_b32_e32 v128, 0, v128, vcc
	v_cmp_nlt_f32_e32 vcc, s2, v127
	s_nop 1
	v_cndmask_b32_e32 v127, v204, v128, vcc
	v_mul_f32_e32 v124, v124, v218
	v_mul_f32_e32 v125, v125, v219
	v_mul_f32_e32 v126, v126, v220
	v_mul_f32_e32 v127, v127, v221
	v_cvt_pk_bf16_f32 v132, v124, v125
	v_cvt_pk_bf16_f32 v133, v126, v127
	ds_write_b64 v120, v[132:133] offset:4672
	ds_read_b128 v[114:117], v119 offset:160
	s_waitcnt lgkmcnt(0)
	v_mul_f32_e32 v124, v121, v114
	v_mul_f32_e32 v125, v121, v115
	v_mul_f32_e32 v126, v121, v116
	v_mul_f32_e32 v127, v121, v117
	v_mul_f32_e32 v128, 0x3fb8aa3b, v124
	v_fma_f32 v129, v124, s96, -v128
	v_rndne_f32_e32 v130, v128
	v_fmac_f32_e32 v129, 0x32a5705f, v124
	v_sub_f32_e32 v128, v128, v130
	v_add_f32_e32 v128, v128, v129
	v_exp_f32_e32 v128, v128
	v_cvt_i32_f32_e32 v129, v130
	v_cmp_ngt_f32_e32 vcc, s68, v124
	v_ldexp_f32 v128, v128, v129
	s_nop 0
	v_cndmask_b32_e32 v128, 0, v128, vcc
	v_cmp_nlt_f32_e32 vcc, s2, v124
	s_nop 1
	v_cndmask_b32_e32 v124, v204, v128, vcc
	v_mul_f32_e32 v128, 0x3fb8aa3b, v125
	v_fma_f32 v129, v125, s96, -v128
	v_rndne_f32_e32 v130, v128
	v_fmac_f32_e32 v129, 0x32a5705f, v125
	v_sub_f32_e32 v128, v128, v130
	v_add_f32_e32 v128, v128, v129
	v_exp_f32_e32 v128, v128
	v_cvt_i32_f32_e32 v129, v130
	v_cmp_ngt_f32_e32 vcc, s68, v125
	v_ldexp_f32 v128, v128, v129
	s_nop 0
	v_cndmask_b32_e32 v128, 0, v128, vcc
	v_cmp_nlt_f32_e32 vcc, s2, v125
	s_nop 1
	v_cndmask_b32_e32 v125, v204, v128, vcc
	v_mul_f32_e32 v128, 0x3fb8aa3b, v126
	v_fma_f32 v129, v126, s96, -v128
	v_rndne_f32_e32 v130, v128
	v_fmac_f32_e32 v129, 0x32a5705f, v126
	v_sub_f32_e32 v128, v128, v130
	v_add_f32_e32 v128, v128, v129
	v_exp_f32_e32 v128, v128
	v_cvt_i32_f32_e32 v129, v130
	v_cmp_ngt_f32_e32 vcc, s68, v126
	v_ldexp_f32 v128, v128, v129
	s_nop 0
	v_cndmask_b32_e32 v128, 0, v128, vcc
	v_cmp_nlt_f32_e32 vcc, s2, v126
	s_nop 1
	v_cndmask_b32_e32 v126, v204, v128, vcc
	v_mul_f32_e32 v128, 0x3fb8aa3b, v127
	v_fma_f32 v129, v127, s96, -v128
	v_rndne_f32_e32 v130, v128
	v_fmac_f32_e32 v129, 0x32a5705f, v127
	v_sub_f32_e32 v128, v128, v130
	v_add_f32_e32 v128, v128, v129
	v_exp_f32_e32 v128, v128
	v_cvt_i32_f32_e32 v129, v130
	v_cmp_ngt_f32_e32 vcc, s68, v127
	v_ldexp_f32 v128, v128, v129
	s_nop 0
	v_cndmask_b32_e32 v128, 0, v128, vcc
	v_cmp_nlt_f32_e32 vcc, s2, v127
	s_nop 1
	v_cndmask_b32_e32 v127, v204, v128, vcc
	v_mul_f32_e32 v124, v124, v158
	v_mul_f32_e32 v125, v125, v159
	v_mul_f32_e32 v126, v126, v160
	v_mul_f32_e32 v127, v127, v161
	v_cvt_pk_bf16_f32 v132, v124, v125
	v_cvt_pk_bf16_f32 v133, v126, v127
	ds_write_b64 v120, v[132:133] offset:80
	v_mul_f32_e32 v124, v122, v114
	v_mul_f32_e32 v125, v122, v115
	v_mul_f32_e32 v126, v122, v116
	v_mul_f32_e32 v127, v122, v117
	v_mul_f32_e32 v128, 0x3fb8aa3b, v124
	v_fma_f32 v129, v124, s96, -v128
	v_rndne_f32_e32 v130, v128
	v_fmac_f32_e32 v129, 0x32a5705f, v124
	v_sub_f32_e32 v128, v128, v130
	v_add_f32_e32 v128, v128, v129
	v_exp_f32_e32 v128, v128
	v_cvt_i32_f32_e32 v129, v130
	v_cmp_ngt_f32_e32 vcc, s68, v124
	v_ldexp_f32 v128, v128, v129
	s_nop 0
	v_cndmask_b32_e32 v128, 0, v128, vcc
	v_cmp_nlt_f32_e32 vcc, s2, v124
	s_nop 1
	v_cndmask_b32_e32 v124, v204, v128, vcc
	v_mul_f32_e32 v128, 0x3fb8aa3b, v125
	v_fma_f32 v129, v125, s96, -v128
	v_rndne_f32_e32 v130, v128
	v_fmac_f32_e32 v129, 0x32a5705f, v125
	v_sub_f32_e32 v128, v128, v130
	v_add_f32_e32 v128, v128, v129
	v_exp_f32_e32 v128, v128
	v_cvt_i32_f32_e32 v129, v130
	v_cmp_ngt_f32_e32 vcc, s68, v125
	v_ldexp_f32 v128, v128, v129
	s_nop 0
	v_cndmask_b32_e32 v128, 0, v128, vcc
	v_cmp_nlt_f32_e32 vcc, s2, v125
	s_nop 1
	v_cndmask_b32_e32 v125, v204, v128, vcc
	v_mul_f32_e32 v128, 0x3fb8aa3b, v126
	v_fma_f32 v129, v126, s96, -v128
	v_rndne_f32_e32 v130, v128
	v_fmac_f32_e32 v129, 0x32a5705f, v126
	v_sub_f32_e32 v128, v128, v130
	v_add_f32_e32 v128, v128, v129
	v_exp_f32_e32 v128, v128
	v_cvt_i32_f32_e32 v129, v130
	v_cmp_ngt_f32_e32 vcc, s68, v126
	v_ldexp_f32 v128, v128, v129
	s_nop 0
	v_cndmask_b32_e32 v128, 0, v128, vcc
	v_cmp_nlt_f32_e32 vcc, s2, v126
	s_nop 1
	v_cndmask_b32_e32 v126, v204, v128, vcc
	v_mul_f32_e32 v128, 0x3fb8aa3b, v127
	v_fma_f32 v129, v127, s96, -v128
	v_rndne_f32_e32 v130, v128
	v_fmac_f32_e32 v129, 0x32a5705f, v127
	v_sub_f32_e32 v128, v128, v130
	v_add_f32_e32 v128, v128, v129
	v_exp_f32_e32 v128, v128
	v_cvt_i32_f32_e32 v129, v130
	v_cmp_ngt_f32_e32 vcc, s68, v127
	v_ldexp_f32 v128, v128, v129
	s_nop 0
	v_cndmask_b32_e32 v128, 0, v128, vcc
	v_cmp_nlt_f32_e32 vcc, s2, v127
	s_nop 1
	v_cndmask_b32_e32 v127, v204, v128, vcc
	v_mul_f32_e32 v124, v124, v222
	v_mul_f32_e32 v125, v125, v223
	v_mul_f32_e32 v126, v126, v224
	v_mul_f32_e32 v127, v127, v225
	v_cvt_pk_bf16_f32 v132, v124, v125
	v_cvt_pk_bf16_f32 v133, v126, v127
	ds_write_b64 v120, v[132:133] offset:4688
	ds_read_b128 v[114:117], v119 offset:192
	s_waitcnt lgkmcnt(0)
	v_mul_f32_e32 v124, v121, v114
	v_mul_f32_e32 v125, v121, v115
	v_mul_f32_e32 v126, v121, v116
	v_mul_f32_e32 v127, v121, v117
	v_mul_f32_e32 v128, 0x3fb8aa3b, v124
	v_fma_f32 v129, v124, s96, -v128
	v_rndne_f32_e32 v130, v128
	v_fmac_f32_e32 v129, 0x32a5705f, v124
	v_sub_f32_e32 v128, v128, v130
	v_add_f32_e32 v128, v128, v129
	v_exp_f32_e32 v128, v128
	v_cvt_i32_f32_e32 v129, v130
	v_cmp_ngt_f32_e32 vcc, s68, v124
	v_ldexp_f32 v128, v128, v129
	s_nop 0
	v_cndmask_b32_e32 v128, 0, v128, vcc
	v_cmp_nlt_f32_e32 vcc, s2, v124
	s_nop 1
	v_cndmask_b32_e32 v124, v204, v128, vcc
	v_mul_f32_e32 v128, 0x3fb8aa3b, v125
	v_fma_f32 v129, v125, s96, -v128
	v_rndne_f32_e32 v130, v128
	v_fmac_f32_e32 v129, 0x32a5705f, v125
	v_sub_f32_e32 v128, v128, v130
	v_add_f32_e32 v128, v128, v129
	v_exp_f32_e32 v128, v128
	v_cvt_i32_f32_e32 v129, v130
	v_cmp_ngt_f32_e32 vcc, s68, v125
	v_ldexp_f32 v128, v128, v129
	s_nop 0
	v_cndmask_b32_e32 v128, 0, v128, vcc
	v_cmp_nlt_f32_e32 vcc, s2, v125
	s_nop 1
	v_cndmask_b32_e32 v125, v204, v128, vcc
	v_mul_f32_e32 v128, 0x3fb8aa3b, v126
	v_fma_f32 v129, v126, s96, -v128
	v_rndne_f32_e32 v130, v128
	v_fmac_f32_e32 v129, 0x32a5705f, v126
	v_sub_f32_e32 v128, v128, v130
	v_add_f32_e32 v128, v128, v129
	v_exp_f32_e32 v128, v128
	v_cvt_i32_f32_e32 v129, v130
	v_cmp_ngt_f32_e32 vcc, s68, v126
	v_ldexp_f32 v128, v128, v129
	s_nop 0
	v_cndmask_b32_e32 v128, 0, v128, vcc
	v_cmp_nlt_f32_e32 vcc, s2, v126
	s_nop 1
	v_cndmask_b32_e32 v126, v204, v128, vcc
	v_mul_f32_e32 v128, 0x3fb8aa3b, v127
	v_fma_f32 v129, v127, s96, -v128
	v_rndne_f32_e32 v130, v128
	v_fmac_f32_e32 v129, 0x32a5705f, v127
	v_sub_f32_e32 v128, v128, v130
	v_add_f32_e32 v128, v128, v129
	v_exp_f32_e32 v128, v128
	v_cvt_i32_f32_e32 v129, v130
	v_cmp_ngt_f32_e32 vcc, s68, v127
	v_ldexp_f32 v128, v128, v129
	s_nop 0
	v_cndmask_b32_e32 v128, 0, v128, vcc
	v_cmp_nlt_f32_e32 vcc, s2, v127
	s_nop 1
	v_cndmask_b32_e32 v127, v204, v128, vcc
	v_mul_f32_e32 v124, v124, v162
	v_mul_f32_e32 v125, v125, v163
	v_mul_f32_e32 v126, v126, v164
	v_mul_f32_e32 v127, v127, v165
	v_cvt_pk_bf16_f32 v132, v124, v125
	v_cvt_pk_bf16_f32 v133, v126, v127
	ds_write_b64 v120, v[132:133] offset:96
	v_mul_f32_e32 v124, v122, v114
	v_mul_f32_e32 v125, v122, v115
	v_mul_f32_e32 v126, v122, v116
	v_mul_f32_e32 v127, v122, v117
	v_mul_f32_e32 v128, 0x3fb8aa3b, v124
	v_fma_f32 v129, v124, s96, -v128
	v_rndne_f32_e32 v130, v128
	v_fmac_f32_e32 v129, 0x32a5705f, v124
	v_sub_f32_e32 v128, v128, v130
	v_add_f32_e32 v128, v128, v129
	v_exp_f32_e32 v128, v128
	v_cvt_i32_f32_e32 v129, v130
	v_cmp_ngt_f32_e32 vcc, s68, v124
	v_ldexp_f32 v128, v128, v129
	s_nop 0
	v_cndmask_b32_e32 v128, 0, v128, vcc
	v_cmp_nlt_f32_e32 vcc, s2, v124
	s_nop 1
	v_cndmask_b32_e32 v124, v204, v128, vcc
	v_mul_f32_e32 v128, 0x3fb8aa3b, v125
	v_fma_f32 v129, v125, s96, -v128
	v_rndne_f32_e32 v130, v128
	v_fmac_f32_e32 v129, 0x32a5705f, v125
	v_sub_f32_e32 v128, v128, v130
	v_add_f32_e32 v128, v128, v129
	v_exp_f32_e32 v128, v128
	v_cvt_i32_f32_e32 v129, v130
	v_cmp_ngt_f32_e32 vcc, s68, v125
	v_ldexp_f32 v128, v128, v129
	s_nop 0
	v_cndmask_b32_e32 v128, 0, v128, vcc
	v_cmp_nlt_f32_e32 vcc, s2, v125
	s_nop 1
	v_cndmask_b32_e32 v125, v204, v128, vcc
	v_mul_f32_e32 v128, 0x3fb8aa3b, v126
	v_fma_f32 v129, v126, s96, -v128
	v_rndne_f32_e32 v130, v128
	v_fmac_f32_e32 v129, 0x32a5705f, v126
	v_sub_f32_e32 v128, v128, v130
	v_add_f32_e32 v128, v128, v129
	v_exp_f32_e32 v128, v128
	v_cvt_i32_f32_e32 v129, v130
	v_cmp_ngt_f32_e32 vcc, s68, v126
	v_ldexp_f32 v128, v128, v129
	s_nop 0
	v_cndmask_b32_e32 v128, 0, v128, vcc
	v_cmp_nlt_f32_e32 vcc, s2, v126
	s_nop 1
	v_cndmask_b32_e32 v126, v204, v128, vcc
	v_mul_f32_e32 v128, 0x3fb8aa3b, v127
	v_fma_f32 v129, v127, s96, -v128
	v_rndne_f32_e32 v130, v128
	v_fmac_f32_e32 v129, 0x32a5705f, v127
	v_sub_f32_e32 v128, v128, v130
	v_add_f32_e32 v128, v128, v129
	v_exp_f32_e32 v128, v128
	v_cvt_i32_f32_e32 v129, v130
	v_cmp_ngt_f32_e32 vcc, s68, v127
	v_ldexp_f32 v128, v128, v129
	s_nop 0
	v_cndmask_b32_e32 v128, 0, v128, vcc
	v_cmp_nlt_f32_e32 vcc, s2, v127
	s_nop 1
	v_cndmask_b32_e32 v127, v204, v128, vcc
	v_mul_f32_e32 v124, v124, v226
	v_mul_f32_e32 v125, v125, v227
	v_mul_f32_e32 v126, v126, v228
	v_mul_f32_e32 v127, v127, v229
	v_cvt_pk_bf16_f32 v132, v124, v125
	v_cvt_pk_bf16_f32 v133, v126, v127
	ds_write_b64 v120, v[132:133] offset:4704
	ds_read_b128 v[114:117], v119 offset:224
	s_waitcnt lgkmcnt(0)
	v_mul_f32_e32 v124, v121, v114
	v_mul_f32_e32 v125, v121, v115
	v_mul_f32_e32 v126, v121, v116
	v_mul_f32_e32 v127, v121, v117
	v_mul_f32_e32 v128, 0x3fb8aa3b, v124
	v_fma_f32 v129, v124, s96, -v128
	v_rndne_f32_e32 v130, v128
	v_fmac_f32_e32 v129, 0x32a5705f, v124
	v_sub_f32_e32 v128, v128, v130
	v_add_f32_e32 v128, v128, v129
	v_exp_f32_e32 v128, v128
	v_cvt_i32_f32_e32 v129, v130
	v_cmp_ngt_f32_e32 vcc, s68, v124
	v_ldexp_f32 v128, v128, v129
	s_nop 0
	v_cndmask_b32_e32 v128, 0, v128, vcc
	v_cmp_nlt_f32_e32 vcc, s2, v124
	s_nop 1
	v_cndmask_b32_e32 v124, v204, v128, vcc
	v_mul_f32_e32 v128, 0x3fb8aa3b, v125
	v_fma_f32 v129, v125, s96, -v128
	v_rndne_f32_e32 v130, v128
	v_fmac_f32_e32 v129, 0x32a5705f, v125
	v_sub_f32_e32 v128, v128, v130
	v_add_f32_e32 v128, v128, v129
	v_exp_f32_e32 v128, v128
	v_cvt_i32_f32_e32 v129, v130
	v_cmp_ngt_f32_e32 vcc, s68, v125
	v_ldexp_f32 v128, v128, v129
	s_nop 0
	v_cndmask_b32_e32 v128, 0, v128, vcc
	v_cmp_nlt_f32_e32 vcc, s2, v125
	s_nop 1
	v_cndmask_b32_e32 v125, v204, v128, vcc
	v_mul_f32_e32 v128, 0x3fb8aa3b, v126
	v_fma_f32 v129, v126, s96, -v128
	v_rndne_f32_e32 v130, v128
	v_fmac_f32_e32 v129, 0x32a5705f, v126
	v_sub_f32_e32 v128, v128, v130
	v_add_f32_e32 v128, v128, v129
	v_exp_f32_e32 v128, v128
	v_cvt_i32_f32_e32 v129, v130
	v_cmp_ngt_f32_e32 vcc, s68, v126
	v_ldexp_f32 v128, v128, v129
	s_nop 0
	v_cndmask_b32_e32 v128, 0, v128, vcc
	v_cmp_nlt_f32_e32 vcc, s2, v126
	s_nop 1
	v_cndmask_b32_e32 v126, v204, v128, vcc
	v_mul_f32_e32 v128, 0x3fb8aa3b, v127
	v_fma_f32 v129, v127, s96, -v128
	v_rndne_f32_e32 v130, v128
	v_fmac_f32_e32 v129, 0x32a5705f, v127
	v_sub_f32_e32 v128, v128, v130
	v_add_f32_e32 v128, v128, v129
	v_exp_f32_e32 v128, v128
	v_cvt_i32_f32_e32 v129, v130
	v_cmp_ngt_f32_e32 vcc, s68, v127
	v_ldexp_f32 v128, v128, v129
	s_nop 0
	v_cndmask_b32_e32 v128, 0, v128, vcc
	v_cmp_nlt_f32_e32 vcc, s2, v127
	s_nop 1
	v_cndmask_b32_e32 v127, v204, v128, vcc
	v_mul_f32_e32 v124, v124, v166
	v_mul_f32_e32 v125, v125, v167
	v_mul_f32_e32 v126, v126, v168
	v_mul_f32_e32 v127, v127, v169
	v_cvt_pk_bf16_f32 v132, v124, v125
	v_cvt_pk_bf16_f32 v133, v126, v127
	ds_write_b64 v120, v[132:133] offset:112
	v_mul_f32_e32 v124, v122, v114
	v_mul_f32_e32 v125, v122, v115
	v_mul_f32_e32 v126, v122, v116
	v_mul_f32_e32 v127, v122, v117
	v_mul_f32_e32 v128, 0x3fb8aa3b, v124
	v_fma_f32 v129, v124, s96, -v128
	v_rndne_f32_e32 v130, v128
	v_fmac_f32_e32 v129, 0x32a5705f, v124
	v_sub_f32_e32 v128, v128, v130
	v_add_f32_e32 v128, v128, v129
	v_exp_f32_e32 v128, v128
	v_cvt_i32_f32_e32 v129, v130
	v_cmp_ngt_f32_e32 vcc, s68, v124
	v_ldexp_f32 v128, v128, v129
	s_nop 0
	v_cndmask_b32_e32 v128, 0, v128, vcc
	v_cmp_nlt_f32_e32 vcc, s2, v124
	s_nop 1
	v_cndmask_b32_e32 v124, v204, v128, vcc
	v_mul_f32_e32 v128, 0x3fb8aa3b, v125
	v_fma_f32 v129, v125, s96, -v128
	v_rndne_f32_e32 v130, v128
	v_fmac_f32_e32 v129, 0x32a5705f, v125
	v_sub_f32_e32 v128, v128, v130
	v_add_f32_e32 v128, v128, v129
	v_exp_f32_e32 v128, v128
	v_cvt_i32_f32_e32 v129, v130
	v_cmp_ngt_f32_e32 vcc, s68, v125
	v_ldexp_f32 v128, v128, v129
	s_nop 0
	v_cndmask_b32_e32 v128, 0, v128, vcc
	v_cmp_nlt_f32_e32 vcc, s2, v125
	s_nop 1
	v_cndmask_b32_e32 v125, v204, v128, vcc
	v_mul_f32_e32 v128, 0x3fb8aa3b, v126
	v_fma_f32 v129, v126, s96, -v128
	v_rndne_f32_e32 v130, v128
	v_fmac_f32_e32 v129, 0x32a5705f, v126
	v_sub_f32_e32 v128, v128, v130
	v_add_f32_e32 v128, v128, v129
	v_exp_f32_e32 v128, v128
	v_cvt_i32_f32_e32 v129, v130
	v_cmp_ngt_f32_e32 vcc, s68, v126
	v_ldexp_f32 v128, v128, v129
	s_nop 0
	v_cndmask_b32_e32 v128, 0, v128, vcc
	v_cmp_nlt_f32_e32 vcc, s2, v126
	s_nop 1
	v_cndmask_b32_e32 v126, v204, v128, vcc
	v_mul_f32_e32 v128, 0x3fb8aa3b, v127
	v_fma_f32 v129, v127, s96, -v128
	v_rndne_f32_e32 v130, v128
	v_fmac_f32_e32 v129, 0x32a5705f, v127
	v_sub_f32_e32 v128, v128, v130
	v_add_f32_e32 v128, v128, v129
	v_exp_f32_e32 v128, v128
	v_cvt_i32_f32_e32 v129, v130
	v_cmp_ngt_f32_e32 vcc, s68, v127
	v_ldexp_f32 v128, v128, v129
	s_nop 0
	v_cndmask_b32_e32 v128, 0, v128, vcc
	v_cmp_nlt_f32_e32 vcc, s2, v127
	s_nop 1
	v_cndmask_b32_e32 v127, v204, v128, vcc
	v_mul_f32_e32 v124, v124, v230
	v_mul_f32_e32 v125, v125, v231
	v_mul_f32_e32 v126, v126, v232
	v_mul_f32_e32 v127, v127, v233
	v_cvt_pk_bf16_f32 v132, v124, v125
	v_cvt_pk_bf16_f32 v133, v126, v127
	ds_write_b64 v120, v[132:133] offset:4720
	v_readlane_b32 s53, v252, 46
	v_readlane_b32 s54, v252, 47
	v_readlane_b32 s55, v252, 48
	v_readlane_b32 s56, v252, 49
	v_readlane_b32 s57, v252, 50
	v_readlane_b32 s58, v252, 51
	v_readlane_b32 s59, v252, 52
	v_readlane_b32 s60, v252, 53
	v_readlane_b32 s61, v252, 54
	v_readlane_b32 s62, v252, 55
	v_readlane_b32 s63, v252, 56
	v_readlane_b32 s64, v252, 57
	v_readlane_b32 s65, v252, 58
	s_mov_b32 s39, s38
	v_lshlrev_b32_e32 v0, 4, v142
	v_and_b32_e32 v0, 0x70, v0
	v_ashrrev_i32_e32 v8, 3, v142
	s_movk_i32 s11, 0x90
	v_mad_u64_u32 v[2:3], s[0:1], v8, s11, v[0:1]
	s_mul_i32 s1, s44, 0x440000
	s_mul_hi_i32 s0, s44, 0x440000
	s_add_u32 s9, s78, s1
	s_addc_u32 s10, s79, s0
	s_and_b64 s[0:1], s[28:29], exec
	s_cselect_b32 s0, 0x40000, 0
	s_add_u32 s9, s9, s0
	s_addc_u32 s10, s10, 0
	s_ashr_i32 s39, s38, 31
	s_lshl_b64 s[0:1], s[38:39], 1
	s_add_u32 s0, s9, s0
	s_addc_u32 s1, s10, s1
	s_waitcnt lgkmcnt(0)
	s_barrier
	ds_read_b128 v[2:5], v2 offset:41216
	v_lshl_add_u64 v[6:7], s[0:1], 0, v[0:1]
	v_add_u32_e32 v8, s8, v8
	s_and_b64 s[0:1], s[28:29], exec
	v_ashrrev_i32_e32 v9, 31, v8
	s_cselect_b32 s9, 12, 8
	v_lshlrev_b64 v[8:9], s9, v[8:9]
	v_lshl_add_u64 v[8:9], v[8:9], 1, v[6:7]
	s_waitcnt lgkmcnt(0)
	global_store_dwordx4 v[8:9], v[2:5], off
	s_nop 1
	v_add_u32_e32 v2, 0x100, v142
	v_ashrrev_i32_e32 v8, 3, v2
	v_mad_u64_u32 v[2:3], s[0:1], v8, s11, v[0:1]
	ds_read_b128 v[2:5], v2 offset:41216
	v_add_u32_e32 v8, s8, v8
	v_ashrrev_i32_e32 v9, 31, v8
	v_lshlrev_b64 v[8:9], s9, v[8:9]
	v_lshl_add_u64 v[8:9], v[8:9], 1, v[6:7]
	s_waitcnt lgkmcnt(0)
	global_store_dwordx4 v[8:9], v[2:5], off
	s_nop 1
	v_add_u32_e32 v2, 0x200, v142
	v_ashrrev_i32_e32 v8, 3, v2
	v_mad_u64_u32 v[2:3], s[0:1], v8, s11, v[0:1]
	ds_read_b128 v[2:5], v2 offset:41216
	v_add_u32_e32 v8, s8, v8
	v_ashrrev_i32_e32 v9, 31, v8
	v_lshlrev_b64 v[8:9], s9, v[8:9]
	v_lshl_add_u64 v[8:9], v[8:9], 1, v[6:7]
	s_waitcnt lgkmcnt(0)
	global_store_dwordx4 v[8:9], v[2:5], off
	s_nop 1
	v_add_u32_e32 v2, 0x300, v142
	v_ashrrev_i32_e32 v8, 3, v2
	v_mad_u64_u32 v[2:3], s[0:1], v8, s11, v[0:1]
	ds_read_b128 v[2:5], v2 offset:41216
	v_add_u32_e32 v8, s8, v8
	v_ashrrev_i32_e32 v9, 31, v8
	v_lshlrev_b64 v[8:9], s9, v[8:9]
	v_lshl_add_u64 v[8:9], v[8:9], 1, v[6:7]
	s_waitcnt lgkmcnt(0)
	global_store_dwordx4 v[8:9], v[2:5], off
	s_nop 1
	v_add_u32_e32 v2, 0x400, v142
	v_ashrrev_i32_e32 v8, 3, v2
	v_mad_u64_u32 v[2:3], s[0:1], v8, s11, v[0:1]
	ds_read_b128 v[2:5], v2 offset:41216
	v_add_u32_e32 v8, s8, v8
	v_ashrrev_i32_e32 v9, 31, v8
	v_lshlrev_b64 v[8:9], s9, v[8:9]
	v_lshl_add_u64 v[8:9], v[8:9], 1, v[6:7]
	s_waitcnt lgkmcnt(0)
	global_store_dwordx4 v[8:9], v[2:5], off
	s_nop 1
	v_add_u32_e32 v2, 0x500, v142
	v_ashrrev_i32_e32 v8, 3, v2
	v_mad_u64_u32 v[2:3], s[0:1], v8, s11, v[0:1]
	ds_read_b128 v[2:5], v2 offset:41216
	v_add_u32_e32 v8, s8, v8
	v_ashrrev_i32_e32 v9, 31, v8
	v_lshlrev_b64 v[8:9], s9, v[8:9]
	v_lshl_add_u64 v[8:9], v[8:9], 1, v[6:7]
	s_waitcnt lgkmcnt(0)
	global_store_dwordx4 v[8:9], v[2:5], off
	s_nop 1
	v_add_u32_e32 v2, 0x600, v142
	v_ashrrev_i32_e32 v8, 3, v2
	v_mad_u64_u32 v[2:3], s[0:1], v8, s11, v[0:1]
	ds_read_b128 v[2:5], v2 offset:41216
	v_add_u32_e32 v8, s8, v8
	v_ashrrev_i32_e32 v9, 31, v8
	v_lshlrev_b64 v[8:9], s9, v[8:9]
	v_lshl_add_u64 v[8:9], v[8:9], 1, v[6:7]
	s_waitcnt lgkmcnt(0)
	global_store_dwordx4 v[8:9], v[2:5], off
	s_nop 1
	v_add_u32_e32 v2, 0x700, v142
	v_ashrrev_i32_e32 v8, 3, v2
	v_mad_u64_u32 v[2:3], s[0:1], v8, s11, v[0:1]
	ds_read_b128 v[2:5], v2 offset:41216
	v_add_u32_e32 v8, s8, v8
	v_ashrrev_i32_e32 v9, 31, v8
	v_lshlrev_b64 v[8:9], s9, v[8:9]
	v_lshl_add_u64 v[6:7], v[8:9], 1, v[6:7]
	s_waitcnt lgkmcnt(0)
	global_store_dwordx4 v[6:7], v[2:5], off
	s_barrier
	s_branch .LBB0_746
